# P7 epilogue: conv row shifts through an LDS strip (exec-masked ds reads, packed fma taps) instead of cndmask+DPP
# baseline (speedup 1.0000x reference)
; #define PG8_LAS __attribute__((address_space(3)))
;     __device__ __forceinline__ void operator()(const f32x4 (&acc)[2][2][4][2], const Unit& u, int wr, int wc, int fr, int fq) const {
;     ...
;         float rs[2][4];
;         load_rs(slots, u.pm * BM + wr * 64, fr, fq, 1.0f, rs);
;         if (fr >= 14) {
; #pragma unroll
;             for (int ai = 0; ai < 2; ++ai)
; #pragma unroll
;                 for (int bj = 0; bj < 2; ++bj)
; #pragma unroll
;                     for (int n = 0; n < 2; ++n) { const f32x4 x = acc[ai][bj][3][n] * rs[ai][3];
;                         *(PG8_LAS f32x4*)(halo + ((ai * 2 + wr) * 2 + (fr - 14)) * 256 + bj * HALF + lcol + 4 * n) = x;
;                         if (ai == 1 && wr == 1) *(f32x4*)(rawh + (size_t)(u.pm * 2 + (fr - 14)) * FF2 + bj * FF + gcol + 4 * n) = x; }
;         }
;         f32x4 w0[2], w1[2], w2[2], bb[2];
; #pragma unroll
;         for (int bj = 0; bj < 2; ++bj) { const int col = bj * FF + gcol;
;             w0[bj] = *(const f32x4*)(cw + col); w1[bj] = *(const f32x4*)(cw + FF2 + col); w2[bj] = *(const f32x4*)(cw + 2 * FF2 + col); bb[bj] = *(const f32x4*)(cb + col); }
;         asm volatile("s_waitcnt lgkmcnt(0)" ::: "memory"); __builtin_amdgcn_s_barrier(); asm volatile("" ::: "memory");
;         unsigned pk_lo[2][4][2];
; #pragma unroll
;         for (int n = 0; n < 2; ++n) {
;             if (n == 1) {
; #pragma unroll
;                 for (int bj = 0; bj < 2; ++bj) { const int col = bj * FF + gcol + 4;
;                     w0[bj] = *(const f32x4*)(cw + col); w1[bj] = *(const f32x4*)(cw + FF2 + col); w2[bj] = *(const f32x4*)(cw + 2 * FF2 + col); bb[bj] = *(const f32x4*)(cb + col); } }
; #pragma unroll
;             for (int ai = 0; ai < 2; ++ai) {
;                 f32x4 pg[2]; const int pb = ai * 2 + wr - 1;
; #pragma unroll
;                 for (int bj = 0; bj < 2; ++bj) { pg[bj] = (f32x4){0.f, 0.f, 0.f, 0.f};
;                     if (pb >= 0 && fr >= 14) pg[bj] = *(const PG8_LAS f32x4*)(halo + (pb * 2 + (fr - 14)) * 256 + bj * HALF + lcol + 4 * n); }
.LBB0_900:
	v_readlane_b32 s18, v255, 37
	v_readlane_b32 s19, v255, 38
	s_lshl_b32 s5, s71, 8
	s_add_i32 s5, s5, s8
	s_lshl_b32 s11, s71, 1
	s_movk_i32 s29, 0x1600
	s_mov_b32 s100, 0xbfb8aa3b
	s_mov_b32 s79, 0
	v_cmp_gt_u32_e64 s[42:43], 2, v206
	v_cmp_lt_u32_e64 s[44:45], 0, v206
	v_cmp_lt_u32_e64 s[82:83], 1, v206
	v_lshl_or_b32 v233, s69, 7, v208
	v_lshlrev_b32_e32 v237, 2, v206
	v_lshlrev_b32_e32 v233, 2, v233
	v_or_b32_e32 v239, s5, v206
	v_add_u32_e32 v235, 0x2c00, v233
	global_load_dwordx4 v[128:131], v233, s[14:15]
	global_load_dwordx4 v[132:135], v233, s[16:17]
	global_load_dwordx4 v[136:139], v233, s[92:93]
	global_load_dwordx4 v[140:143], v233, s[60:61]
	global_load_dwordx4 v[144:147], v235, s[14:15]
	global_load_dwordx4 v[148:151], v235, s[16:17]
	global_load_dwordx4 v[152:155], v235, s[92:93]
	global_load_dwordx4 v[156:159], v235, s[60:61]
	v_lshrrev_b32_e32 v243, 1, v233
	v_add_u32_e32 v241, s11, v206
	v_mad_u32_u24 v239, v239, s29, v243
	v_mad_u32_u24 v241, v241, s70, v233
	s_cmp_eq_u32 s101, s71
	v_add_u32_e32 v249, 0x2c00, v241
	s_cbranch_scc1 .Lp7_rsok
	v_or_b32_e32 v229, s5, v209
	v_lshlrev_b32_e32 v229, 6, v229
	v_add_u32_e32 v231, 0x2000, v229
	global_load_dwordx4 v[160:163], v229, s[26:27]
	global_load_dwordx4 v[164:167], v229, s[26:27] offset:16
	global_load_dwordx4 v[178:181], v229, s[26:27] offset:32
	global_load_dwordx4 v[182:185], v229, s[26:27] offset:48
	global_load_dwordx4 v[186:189], v231, s[26:27]
	global_load_dwordx4 v[194:197], v231, s[26:27] offset:16
	global_load_dwordx4 v[198:201], v231, s[26:27] offset:32
	global_load_dwordx4 v[202:205], v231, s[26:27] offset:48
	s_waitcnt vmcnt(0)
	v_pk_add_f32 v[162:163], v[162:163], v[166:167]
	v_pk_add_f32 v[188:189], v[188:189], v[196:197]
	v_pk_add_f32 v[160:161], v[160:161], v[164:165]
	v_pk_add_f32 v[186:187], v[186:187], v[194:195]
	v_pk_add_f32 v[164:165], v[180:181], v[184:185]
	v_pk_add_f32 v[194:195], v[200:201], v[204:205]
	v_pk_add_f32 v[166:167], v[178:179], v[182:183]
	v_pk_add_f32 v[196:197], v[198:199], v[202:203]
	v_pk_add_f32 v[162:163], v[162:163], v[164:165]
	v_pk_add_f32 v[188:189], v[188:189], v[194:195]
	v_pk_add_f32 v[160:161], v[160:161], v[166:167]
	v_pk_add_f32 v[186:187], v[186:187], v[196:197]
	v_add_f32_e32 v160, v160, v161
	v_add_f32_e32 v186, v186, v187
	v_add_f32_e32 v161, v162, v163
	v_add_f32_e32 v187, v188, v189
	v_add_f32_e32 v160, v160, v161
	v_add_f32_e32 v186, v186, v187
	v_fmamk_f32 v160, v160, 0x3a800000, v244
	v_fmamk_f32 v186, v186, 0x3a800000, v244
	v_rsq_f32_e32 v160, v160
	v_rsq_f32_e32 v186, v186
	ds_bpermute_b32 v228, v237, v160
	ds_bpermute_b32 v230, v237, v160 offset:64
	ds_bpermute_b32 v232, v237, v160 offset:128
	ds_bpermute_b32 v234, v237, v160 offset:192
	ds_bpermute_b32 v236, v237, v186
	ds_bpermute_b32 v238, v237, v186 offset:64
	ds_bpermute_b32 v240, v237, v186 offset:128
	ds_bpermute_b32 v248, v237, v186 offset:192
	s_mov_b32 s101, s71
.Lp7_rsok:
	s_waitcnt lgkmcnt(0)
	v_lshrrev_b32_e32 v220, 3, v208
	s_add_i32 s86, s75, 0xc100
	v_lshrrev_b32_e32 v221, 2, v206
	v_xor_b32_e32 v221, v221, v220
	v_and_b32_e32 v221, 3, v221
	v_lshlrev_b32_e32 v221, 4, v221
	v_lshl_add_u32 v221, v206, 6, v221
	v_add_u32_e32 v212, s86, v221
	v_add_u32_e32 v223, -1, v206
	v_and_b32_e32 v223, 15, v223
	v_lshrrev_b32_e32 v221, 2, v223
	v_xor_b32_e32 v221, v221, v220
	v_and_b32_e32 v221, 3, v221
	v_lshlrev_b32_e32 v221, 4, v221
	v_lshl_add_u32 v221, v223, 6, v221
	v_add_u32_e32 v235, s86, v221
	v_add_u32_e32 v223, -2, v206
	v_and_b32_e32 v223, 15, v223
	v_lshrrev_b32_e32 v221, 2, v223
	v_xor_b32_e32 v221, v221, v220
	v_and_b32_e32 v221, 3, v221
	v_lshlrev_b32_e32 v221, 4, v221
	v_lshl_add_u32 v221, v223, 6, v221
	v_add_u32_e32 v237, s86, v221
	v_pk_mul_f32 v[100:101], v[100:101], v[234:235] op_sel_hi:[1,0]
	v_pk_mul_f32 v[102:103], v[102:103], v[234:235] op_sel_hi:[1,0]
	v_pk_mul_f32 v[36:37], v[36:37], v[234:235] op_sel_hi:[1,0]
	v_pk_mul_f32 v[38:39], v[38:39], v[234:235] op_sel_hi:[1,0]
	v_pk_mul_f32 v[96:97], v[96:97], v[234:235] op_sel_hi:[1,0]
	v_pk_mul_f32 v[98:99], v[98:99], v[234:235] op_sel_hi:[1,0]
	v_pk_mul_f32 v[32:33], v[32:33], v[234:235] op_sel_hi:[1,0]
	v_pk_mul_f32 v[34:35], v[34:35], v[234:235] op_sel_hi:[1,0]
	v_pk_mul_f32 v[68:69], v[68:69], v[248:249] op_sel_hi:[1,0]
	v_pk_mul_f32 v[70:71], v[70:71], v[248:249] op_sel_hi:[1,0]
	v_pk_mul_f32 v[4:5], v[4:5], v[248:249] op_sel_hi:[1,0]
	v_pk_mul_f32 v[6:7], v[6:7], v[248:249] op_sel_hi:[1,0]
	v_pk_mul_f32 v[64:65], v[64:65], v[248:249] op_sel_hi:[1,0]
	v_pk_mul_f32 v[66:67], v[66:67], v[248:249] op_sel_hi:[1,0]
	v_pk_mul_f32 v[0:1], v[0:1], v[248:249] op_sel_hi:[1,0]
	v_pk_mul_f32 v[2:3], v[2:3], v[248:249] op_sel_hi:[1,0]
	s_mov_b64 s[0:1], exec
	s_andn2_b64 exec, exec, s[40:41]
	ds_write_b128 v211, v[100:103]
	ds_write_b128 v211, v[36:39] offset:16
	ds_write_b128 v211, v[96:99] offset:512
	ds_write_b128 v211, v[32:35] offset:528
	ds_write_b128 v211, v[68:71] offset:4096
	ds_write_b128 v211, v[4:7] offset:4112
	ds_write_b128 v211, v[64:67] offset:4608
	ds_write_b128 v211, v[0:3] offset:4624
	s_mov_b64 exec, s[0:1]
	s_waitcnt lgkmcnt(0)
	s_barrier
	s_and_b64 vcc, exec, s[94:95]
	s_cbranch_vccnz .Lp7_hz0
	ds_read_b128 v[160:163], v213
	ds_read_b128 v[164:167], v213 offset:512
	s_branch .Lp7_hr0

; __device__ __forceinline__ unsigned cvt_pk_bf16(float lo, float hi) { unsigned r; asm volatile("v_cvt_pk_bf16_f32 %0, %1, %2" : "=v"(r) : "v"(lo), "v"(hi)); return r; }
; __device__ __forceinline__ float dpp_ror1(float x) { return __int_as_float(__builtin_amdgcn_update_dpp(0, __float_as_int(x), 0x121, 0xf, 0xf, false)); }
; __device__ __forceinline__ float dpp_ror2(float x) { return __int_as_float(__builtin_amdgcn_update_dpp(0, __float_as_int(x), 0x122, 0xf, 0xf, false)); }
;     __device__ __forceinline__ void operator()(const f32x4 (&acc)[2][2][4][2], const Unit& u, int wr, int wc, int fr, int fq) const {
;     ...
;                 for (int m = 0; m < 4; ++m) {
;                     f32x4 cur[2], h[2];
; #pragma unroll
;                     for (int bj = 0; bj < 2; ++bj) { cur[bj] = acc[ai][bj][m][n] * rs[ai][m]; f32x4 x1, x2;
; #pragma unroll
;                         for (int e = 0; e < 4; ++e) { const float c1 = dpp_ror1(cur[bj][e]), p1 = dpp_ror1(pg[bj][e]), c2 = dpp_ror2(cur[bj][e]), p2 = dpp_ror2(pg[bj][e]);
;                             x1[e] = fr >= 1 ? c1 : p1; x2[e] = fr >= 2 ? c2 : p2; }
;                         h[bj] = bb[bj] + w0[bj] * x2 + w1[bj] * x1 + w2[bj] * cur[bj]; }
;                     if (ai == 0 && wr == 0 && m == 0 && fr < 2) {
;                         *(f32x4*)(hc0 + (size_t)(u.pm * 2 + fr) * FF2 + gcol + 4 * n) = h[0]; *(f32x4*)(hc0 + (size_t)(u.pm * 2 + fr) * FF2 + FF + gcol + 4 * n) = h[1]; }
;                     f32x4 a;
; #pragma unroll
;                     for (int e = 0; e < 4; ++e) { const float g = h[0][e]; a[e] = g * __builtin_amdgcn_rcpf(1.0f + __builtin_amdgcn_exp2f(-1.4426950408889634f * g)) * h[1][e]; }
;                     const unsigned p0 = cvt_pk_bf16(a[0], a[1]), p1 = cvt_pk_bf16(a[2], a[3]);
;                     if (n == 0) { pk_lo[ai][m][0] = p0; pk_lo[ai][m][1] = p1; }
;                     else { u32x4 w; w.x = pk_lo[ai][m][0]; w.y = pk_lo[ai][m][1]; w.z = p0; w.w = p1;
;                         *(u32x4*)(act + (size_t)(u.pm * BM + ai * HALF + wr * 64 + m * 16 + fr) * FF + gcol) = w; }
.Lp7_hr0:
	ds_read_b128 v[178:181], v214
	ds_read_b128 v[182:185], v214 offset:512
	v_pk_mul_f32 v[124:125], v[124:125], v[228:229] op_sel_hi:[1,0]
	v_pk_mul_f32 v[126:127], v[126:127], v[228:229] op_sel_hi:[1,0]
	v_pk_mul_f32 v[120:121], v[120:121], v[228:229] op_sel_hi:[1,0]
	v_pk_mul_f32 v[122:123], v[122:123], v[228:229] op_sel_hi:[1,0]
	v_pk_mul_f32 v[116:117], v[116:117], v[230:231] op_sel_hi:[1,0]
	v_pk_mul_f32 v[118:119], v[118:119], v[230:231] op_sel_hi:[1,0]
	v_pk_mul_f32 v[112:113], v[112:113], v[230:231] op_sel_hi:[1,0]
	v_pk_mul_f32 v[114:115], v[114:115], v[230:231] op_sel_hi:[1,0]
	v_pk_mul_f32 v[108:109], v[108:109], v[232:233] op_sel_hi:[1,0]
	v_pk_mul_f32 v[110:111], v[110:111], v[232:233] op_sel_hi:[1,0]
	v_pk_mul_f32 v[104:105], v[104:105], v[232:233] op_sel_hi:[1,0]
	v_pk_mul_f32 v[106:107], v[106:107], v[232:233] op_sel_hi:[1,0]
	v_pk_mul_f32 v[92:93], v[92:93], v[236:237] op_sel_hi:[1,0]
	v_pk_mul_f32 v[94:95], v[94:95], v[236:237] op_sel_hi:[1,0]
	v_pk_mul_f32 v[88:89], v[88:89], v[236:237] op_sel_hi:[1,0]
	v_pk_mul_f32 v[90:91], v[90:91], v[236:237] op_sel_hi:[1,0]
	v_pk_mul_f32 v[84:85], v[84:85], v[238:239] op_sel_hi:[1,0]
	v_pk_mul_f32 v[86:87], v[86:87], v[238:239] op_sel_hi:[1,0]
	v_pk_mul_f32 v[80:81], v[80:81], v[238:239] op_sel_hi:[1,0]
	v_pk_mul_f32 v[82:83], v[82:83], v[238:239] op_sel_hi:[1,0]
	v_pk_mul_f32 v[76:77], v[76:77], v[240:241] op_sel_hi:[1,0]
	v_pk_mul_f32 v[78:79], v[78:79], v[240:241] op_sel_hi:[1,0]
	v_pk_mul_f32 v[72:73], v[72:73], v[240:241] op_sel_hi:[1,0]
	v_pk_mul_f32 v[74:75], v[74:75], v[240:241] op_sel_hi:[1,0]
	v_pk_mul_f32 v[60:61], v[60:61], v[228:229] op_sel_hi:[1,0]
	v_pk_mul_f32 v[62:63], v[62:63], v[228:229] op_sel_hi:[1,0]
	v_pk_mul_f32 v[56:57], v[56:57], v[228:229] op_sel_hi:[1,0]
	v_pk_mul_f32 v[58:59], v[58:59], v[228:229] op_sel_hi:[1,0]
	v_pk_mul_f32 v[52:53], v[52:53], v[230:231] op_sel_hi:[1,0]
	v_pk_mul_f32 v[54:55], v[54:55], v[230:231] op_sel_hi:[1,0]
	v_pk_mul_f32 v[48:49], v[48:49], v[230:231] op_sel_hi:[1,0]
	v_pk_mul_f32 v[50:51], v[50:51], v[230:231] op_sel_hi:[1,0]
	v_pk_mul_f32 v[44:45], v[44:45], v[232:233] op_sel_hi:[1,0]
	v_pk_mul_f32 v[46:47], v[46:47], v[232:233] op_sel_hi:[1,0]
	v_pk_mul_f32 v[40:41], v[40:41], v[232:233] op_sel_hi:[1,0]
	v_pk_mul_f32 v[42:43], v[42:43], v[232:233] op_sel_hi:[1,0]
	v_pk_mul_f32 v[28:29], v[28:29], v[236:237] op_sel_hi:[1,0]
	v_pk_mul_f32 v[30:31], v[30:31], v[236:237] op_sel_hi:[1,0]
	v_pk_mul_f32 v[24:25], v[24:25], v[236:237] op_sel_hi:[1,0]
	v_pk_mul_f32 v[26:27], v[26:27], v[236:237] op_sel_hi:[1,0]
	v_pk_mul_f32 v[20:21], v[20:21], v[238:239] op_sel_hi:[1,0]
	v_pk_mul_f32 v[22:23], v[22:23], v[238:239] op_sel_hi:[1,0]
	v_pk_mul_f32 v[16:17], v[16:17], v[238:239] op_sel_hi:[1,0]
	v_pk_mul_f32 v[18:19], v[18:19], v[238:239] op_sel_hi:[1,0]
	v_pk_mul_f32 v[12:13], v[12:13], v[240:241] op_sel_hi:[1,0]
	v_pk_mul_f32 v[14:15], v[14:15], v[240:241] op_sel_hi:[1,0]
	v_pk_mul_f32 v[8:9], v[8:9], v[240:241] op_sel_hi:[1,0]
	v_pk_mul_f32 v[10:11], v[10:11], v[240:241] op_sel_hi:[1,0]
	s_waitcnt vmcnt(0) lgkmcnt(0)
	v_pk_fma_f32 v[220:221], v[136:137], v[124:125], v[140:141]
	v_pk_fma_f32 v[222:223], v[138:139], v[126:127], v[142:143]
	v_pk_fma_f32 v[224:225], v[152:153], v[120:121], v[156:157]
	v_pk_fma_f32 v[226:227], v[154:155], v[122:123], v[158:159]
	s_andn2_b64 exec, exec, s[40:41]
	ds_write_b128 v212, v[160:163]
	ds_write_b128 v212, v[164:167] offset:8192
	s_mov_b64 exec, -1
	s_mov_b64 exec, s[42:43]
	ds_read_b64 v[188:189], v235
	ds_read_b64 v[196:197], v235 offset:8
	ds_read_b64 v[200:201], v237
	ds_read_b64 v[204:205], v237 offset:8
	s_mov_b64 exec, -1
	ds_write_b128 v212, v[124:127]
	s_mov_b64 exec, s[44:45]
	ds_read_b64 v[188:189], v235
	ds_read_b64 v[196:197], v235 offset:8
	s_mov_b64 exec, s[82:83]
	ds_read_b64 v[200:201], v237
	ds_read_b64 v[204:205], v237 offset:8
	s_mov_b64 exec, -1
	s_waitcnt lgkmcnt(0)
	v_pk_fma_f32 v[220:221], v[132:133], v[188:189], v[220:221]
	v_pk_fma_f32 v[222:223], v[134:135], v[196:197], v[222:223]
	v_pk_fma_f32 v[220:221], v[128:129], v[200:201], v[220:221]
	v_pk_fma_f32 v[222:223], v[130:131], v[204:205], v[222:223]
	s_mov_b64 exec, s[42:43]
	ds_read_b64 v[188:189], v235 offset:8192
	ds_read_b64 v[196:197], v235 offset:8200
	ds_read_b64 v[200:201], v237 offset:8192
	ds_read_b64 v[204:205], v237 offset:8200
	s_mov_b64 exec, -1
	ds_write_b128 v212, v[120:123] offset:8192
	s_mov_b64 exec, s[44:45]
	ds_read_b64 v[188:189], v235 offset:8192
	ds_read_b64 v[196:197], v235 offset:8200
	s_mov_b64 exec, s[82:83]
	ds_read_b64 v[200:201], v237 offset:8192
	ds_read_b64 v[204:205], v237 offset:8200
	s_mov_b64 exec, -1
	s_waitcnt lgkmcnt(0)
	v_pk_fma_f32 v[224:225], v[148:149], v[188:189], v[224:225]
	v_pk_fma_f32 v[226:227], v[150:151], v[196:197], v[226:227]
	v_pk_fma_f32 v[224:225], v[144:145], v[200:201], v[224:225]
	v_pk_fma_f32 v[226:227], v[146:147], v[204:205], v[226:227]
	s_and_saveexec_b64 s[0:1], s[12:13]
	global_store_dwordx4 v241, v[220:223], s[84:85]
	global_store_dwordx4 v249, v[224:227], s[84:85]
	s_or_b64 exec, exec, s[0:1]
	v_pk_mul_f32 v[190:191], v[220:221], s[100:101] op_sel_hi:[1,0]
	v_pk_mul_f32 v[250:251], v[222:223], s[100:101] op_sel_hi:[1,0]
	v_exp_f32_e32 v190, v190
	v_exp_f32_e32 v191, v191
	v_exp_f32_e32 v250, v250
	v_exp_f32_e32 v251, v251
	v_pk_mul_f32 v[220:221], v[220:221], v[224:225]
	v_pk_mul_f32 v[222:223], v[222:223], v[226:227]
	v_pk_add_f32 v[190:191], v[190:191], 1.0 op_sel_hi:[1,0]
	v_pk_add_f32 v[250:251], v[250:251], 1.0 op_sel_hi:[1,0]
	v_rcp_f32_e32 v190, v190
	v_rcp_f32_e32 v191, v191
	v_rcp_f32_e32 v250, v250
	v_rcp_f32_e32 v251, v251
	v_pk_mul_f32 v[220:221], v[220:221], v[190:191]
	v_pk_mul_f32 v[222:223], v[222:223], v[250:251]
	v_cvt_pk_bf16_f32 v186, v220, v221
	v_cvt_pk_bf16_f32 v187, v222, v223
	s_and_b64 vcc, exec, s[20:21]
	s_cbranch_vccnz .Lp7_norawh
	s_mov_b64 s[0:1], exec
	s_andn2_b64 exec, exec, s[40:41]
	v_add_u32_e32 v229, s11, v210
	v_mad_u32_u24 v229, v229, s70, v233
	v_add_u32_e32 v231, 0x2c00, v229
	global_store_dwordx4 v229, v[68:71], s[18:19]
	global_store_dwordx4 v229, v[4:7], s[18:19] offset:16
	global_store_dwordx4 v231, v[64:67], s[18:19]
	global_store_dwordx4 v231, v[0:3], s[18:19] offset:16
	s_mov_b64 exec, s[0:1]
; __device__ __forceinline__ unsigned cvt_pk_bf16(float lo, float hi) { unsigned r; asm volatile("v_cvt_pk_bf16_f32 %0, %1, %2" : "=v"(r) : "v"(lo), "v"(hi)); return r; }
; __device__ __forceinline__ float dpp_ror1(float x) { return __int_as_float(__builtin_amdgcn_update_dpp(0, __float_as_int(x), 0x121, 0xf, 0xf, false)); }
; __device__ __forceinline__ float dpp_ror2(float x) { return __int_as_float(__builtin_amdgcn_update_dpp(0, __float_as_int(x), 0x122, 0xf, 0xf, false)); }
;     __device__ __forceinline__ void operator()(const f32x4 (&acc)[2][2][4][2], const Unit& u, int wr, int wc, int fr, int fq) const {
;     ...
;                 for (int m = 0; m < 4; ++m) {
;                     f32x4 cur[2], h[2];
; #pragma unroll
;                     for (int bj = 0; bj < 2; ++bj) { cur[bj] = acc[ai][bj][m][n] * rs[ai][m]; f32x4 x1, x2;
; #pragma unroll
;                         for (int e = 0; e < 4; ++e) { const float c1 = dpp_ror1(cur[bj][e]), p1 = dpp_ror1(pg[bj][e]), c2 = dpp_ror2(cur[bj][e]), p2 = dpp_ror2(pg[bj][e]);
;                             x1[e] = fr >= 1 ? c1 : p1; x2[e] = fr >= 2 ? c2 : p2; }
;                         h[bj] = bb[bj] + w0[bj] * x2 + w1[bj] * x1 + w2[bj] * cur[bj]; }
;                     if (ai == 0 && wr == 0 && m == 0 && fr < 2) {
;                         *(f32x4*)(hc0 + (size_t)(u.pm * 2 + fr) * FF2 + gcol + 4 * n) = h[0]; *(f32x4*)(hc0 + (size_t)(u.pm * 2 + fr) * FF2 + FF + gcol + 4 * n) = h[1]; }
;                     f32x4 a;
; #pragma unroll
;                     for (int e = 0; e < 4; ++e) { const float g = h[0][e]; a[e] = g * __builtin_amdgcn_rcpf(1.0f + __builtin_amdgcn_exp2f(-1.4426950408889634f * g)) * h[1][e]; }
;                     const unsigned p0 = cvt_pk_bf16(a[0], a[1]), p1 = cvt_pk_bf16(a[2], a[3]);
;                     if (n == 0) { pk_lo[ai][m][0] = p0; pk_lo[ai][m][1] = p1; }
;                     else { u32x4 w; w.x = pk_lo[ai][m][0]; w.y = pk_lo[ai][m][1]; w.z = p0; w.w = p1;
;                         *(u32x4*)(act + (size_t)(u.pm * BM + ai * HALF + wr * 64 + m * 16 + fr) * FF + gcol) = w; }
;                     pg[0] = cur[0]; pg[1] = cur[1];
.Lp7_norawh:
	v_pk_fma_f32 v[220:221], v[136:137], v[116:117], v[140:141]
	v_pk_fma_f32 v[222:223], v[138:139], v[118:119], v[142:143]
	v_pk_fma_f32 v[224:225], v[152:153], v[112:113], v[156:157]
	v_pk_fma_f32 v[226:227], v[154:155], v[114:115], v[158:159]
	s_mov_b64 exec, s[42:43]
	ds_read_b64 v[188:189], v235
	ds_read_b64 v[196:197], v235 offset:8
	ds_read_b64 v[200:201], v237
	ds_read_b64 v[204:205], v237 offset:8
	s_mov_b64 exec, -1
	ds_write_b128 v212, v[116:119]
	s_mov_b64 exec, s[44:45]
	ds_read_b64 v[188:189], v235
	ds_read_b64 v[196:197], v235 offset:8
	s_mov_b64 exec, s[82:83]
	ds_read_b64 v[200:201], v237
	ds_read_b64 v[204:205], v237 offset:8
	s_mov_b64 exec, -1
	s_waitcnt lgkmcnt(0)
	v_pk_fma_f32 v[220:221], v[132:133], v[188:189], v[220:221]
	v_pk_fma_f32 v[222:223], v[134:135], v[196:197], v[222:223]
	v_pk_fma_f32 v[220:221], v[128:129], v[200:201], v[220:221]
	v_pk_fma_f32 v[222:223], v[130:131], v[204:205], v[222:223]
	s_mov_b64 exec, s[42:43]
	ds_read_b64 v[188:189], v235 offset:8192
	ds_read_b64 v[196:197], v235 offset:8200
	ds_read_b64 v[200:201], v237 offset:8192
	ds_read_b64 v[204:205], v237 offset:8200
	s_mov_b64 exec, -1
	ds_write_b128 v212, v[112:115] offset:8192
	s_mov_b64 exec, s[44:45]
	ds_read_b64 v[188:189], v235 offset:8192
	ds_read_b64 v[196:197], v235 offset:8200
	s_mov_b64 exec, s[82:83]
	ds_read_b64 v[200:201], v237 offset:8192
	ds_read_b64 v[204:205], v237 offset:8200
	s_mov_b64 exec, -1
	s_waitcnt lgkmcnt(0)
	v_pk_fma_f32 v[224:225], v[148:149], v[188:189], v[224:225]
	v_pk_fma_f32 v[226:227], v[150:151], v[196:197], v[226:227]
	v_pk_fma_f32 v[224:225], v[144:145], v[200:201], v[224:225]
	v_pk_fma_f32 v[226:227], v[146:147], v[204:205], v[226:227]
	v_pk_mul_f32 v[190:191], v[220:221], s[100:101] op_sel_hi:[1,0]
	v_pk_mul_f32 v[250:251], v[222:223], s[100:101] op_sel_hi:[1,0]
	v_exp_f32_e32 v190, v190
	v_exp_f32_e32 v191, v191
	v_exp_f32_e32 v250, v250
	v_exp_f32_e32 v251, v251
	v_pk_mul_f32 v[220:221], v[220:221], v[224:225]
	v_pk_mul_f32 v[222:223], v[222:223], v[226:227]
	v_pk_add_f32 v[190:191], v[190:191], 1.0 op_sel_hi:[1,0]
	v_pk_add_f32 v[250:251], v[250:251], 1.0 op_sel_hi:[1,0]
	v_rcp_f32_e32 v190, v190
	v_rcp_f32_e32 v191, v191
	v_rcp_f32_e32 v250, v250
	v_rcp_f32_e32 v251, v251
	v_pk_mul_f32 v[220:221], v[220:221], v[190:191]
	v_pk_mul_f32 v[222:223], v[222:223], v[250:251]
	v_cvt_pk_bf16_f32 v194, v220, v221
	v_cvt_pk_bf16_f32 v195, v222, v223
	v_pk_fma_f32 v[220:221], v[136:137], v[108:109], v[140:141]
	v_pk_fma_f32 v[222:223], v[138:139], v[110:111], v[142:143]
	v_pk_fma_f32 v[224:225], v[152:153], v[104:105], v[156:157]
	v_pk_fma_f32 v[226:227], v[154:155], v[106:107], v[158:159]
	s_mov_b64 exec, s[42:43]
	ds_read_b64 v[188:189], v235
	ds_read_b64 v[196:197], v235 offset:8
	ds_read_b64 v[200:201], v237
	ds_read_b64 v[204:205], v237 offset:8
	s_mov_b64 exec, -1
	ds_write_b128 v212, v[108:111]
	s_mov_b64 exec, s[44:45]
	ds_read_b64 v[188:189], v235
	ds_read_b64 v[196:197], v235 offset:8
	s_mov_b64 exec, s[82:83]
	ds_read_b64 v[200:201], v237
	ds_read_b64 v[204:205], v237 offset:8
	s_mov_b64 exec, -1
	s_waitcnt lgkmcnt(0)
	v_pk_fma_f32 v[220:221], v[132:133], v[188:189], v[220:221]
	v_pk_fma_f32 v[222:223], v[134:135], v[196:197], v[222:223]
	v_pk_fma_f32 v[220:221], v[128:129], v[200:201], v[220:221]
	v_pk_fma_f32 v[222:223], v[130:131], v[204:205], v[222:223]
	s_mov_b64 exec, s[42:43]
	ds_read_b64 v[188:189], v235 offset:8192
	ds_read_b64 v[196:197], v235 offset:8200
	ds_read_b64 v[200:201], v237 offset:8192
	ds_read_b64 v[204:205], v237 offset:8200
	s_mov_b64 exec, -1
	ds_write_b128 v212, v[104:107] offset:8192
	s_mov_b64 exec, s[44:45]
	ds_read_b64 v[188:189], v235 offset:8192
	ds_read_b64 v[196:197], v235 offset:8200
	s_mov_b64 exec, s[82:83]
	ds_read_b64 v[200:201], v237 offset:8192
	ds_read_b64 v[204:205], v237 offset:8200
	s_mov_b64 exec, -1
	s_waitcnt lgkmcnt(0)
	v_pk_fma_f32 v[224:225], v[148:149], v[188:189], v[224:225]
	v_pk_fma_f32 v[226:227], v[150:151], v[196:197], v[226:227]
	v_pk_fma_f32 v[224:225], v[144:145], v[200:201], v[224:225]
	v_pk_fma_f32 v[226:227], v[146:147], v[204:205], v[226:227]
	v_pk_mul_f32 v[190:191], v[220:221], s[100:101] op_sel_hi:[1,0]
	v_pk_mul_f32 v[250:251], v[222:223], s[100:101] op_sel_hi:[1,0]
	v_exp_f32_e32 v190, v190
	v_exp_f32_e32 v191, v191
	v_exp_f32_e32 v250, v250
	v_exp_f32_e32 v251, v251
	v_pk_mul_f32 v[220:221], v[220:221], v[224:225]
	v_pk_mul_f32 v[222:223], v[222:223], v[226:227]
	v_pk_add_f32 v[190:191], v[190:191], 1.0 op_sel_hi:[1,0]
	v_pk_add_f32 v[250:251], v[250:251], 1.0 op_sel_hi:[1,0]
	v_rcp_f32_e32 v190, v190
	v_rcp_f32_e32 v191, v191
	v_rcp_f32_e32 v250, v250
	v_rcp_f32_e32 v251, v251
	v_pk_mul_f32 v[220:221], v[220:221], v[190:191]
	v_pk_mul_f32 v[222:223], v[222:223], v[250:251]
	v_cvt_pk_bf16_f32 v198, v220, v221
	v_cvt_pk_bf16_f32 v199, v222, v223
	v_pk_fma_f32 v[220:221], v[136:137], v[100:101], v[140:141]
	v_pk_fma_f32 v[222:223], v[138:139], v[102:103], v[142:143]
	v_pk_fma_f32 v[224:225], v[152:153], v[96:97], v[156:157]
	v_pk_fma_f32 v[226:227], v[154:155], v[98:99], v[158:159]
	s_mov_b64 exec, s[42:43]
	ds_read_b64 v[188:189], v235
	ds_read_b64 v[196:197], v235 offset:8
	ds_read_b64 v[200:201], v237
	ds_read_b64 v[204:205], v237 offset:8
	s_mov_b64 exec, -1
	ds_write_b128 v212, v[100:103]
	s_mov_b64 exec, s[44:45]
	ds_read_b64 v[188:189], v235
	ds_read_b64 v[196:197], v235 offset:8
	s_mov_b64 exec, s[82:83]
	ds_read_b64 v[200:201], v237
	ds_read_b64 v[204:205], v237 offset:8
	s_mov_b64 exec, -1
	s_waitcnt lgkmcnt(0)
;     __device__ __forceinline__ void operator()(const f32x4 (&acc)[2][2][4][2], const Unit& u, int wr, int wc, int fr, int fq) const {
;     ...
;         for (int n = 0; n < 2; ++n) {
;             if (n == 1) {
; #pragma unroll
;                 for (int bj = 0; bj < 2; ++bj) { const int col = bj * FF + gcol + 4;
;                     w0[bj] = *(const f32x4*)(cw + col); w1[bj] = *(const f32x4*)(cw + FF2 + col); w2[bj] = *(const f32x4*)(cw + 2 * FF2 + col); bb[bj] = *(const f32x4*)(cb + col); } }
; #pragma unroll
;             for (int ai = 0; ai < 2; ++ai) {
;                 f32x4 pg[2]; const int pb = ai * 2 + wr - 1;
; #pragma unroll
;                 for (int bj = 0; bj < 2; ++bj) { pg[bj] = (f32x4){0.f, 0.f, 0.f, 0.f};
;                     if (pb >= 0 && fr >= 14) pg[bj] = *(const PG8_LAS f32x4*)(halo + (pb * 2 + (fr - 14)) * 256 + bj * HALF + lcol + 4 * n); }
; #pragma unroll
;                 for (int m = 0; m < 4; ++m) {
;                     f32x4 cur[2], h[2];
; #pragma unroll
;                     for (int bj = 0; bj < 2; ++bj) { cur[bj] = acc[ai][bj][m][n] * rs[ai][m]; f32x4 x1, x2;
; #pragma unroll
;                         for (int e = 0; e < 4; ++e) { const float c1 = dpp_ror1(cur[bj][e]), p1 = dpp_ror1(pg[bj][e]), c2 = dpp_ror2(cur[bj][e]), p2 = dpp_ror2(pg[bj][e]);
;                             x1[e] = fr >= 1 ? c1 : p1; x2[e] = fr >= 2 ? c2 : p2; }
;                         h[bj] = bb[bj] + w0[bj] * x2 + w1[bj] * x1 + w2[bj] * cur[bj]; }
;                     if (ai == 0 && wr == 0 && m == 0 && fr < 2) {
;                         *(f32x4*)(hc0 + (size_t)(u.pm * 2 + fr) * FF2 + gcol + 4 * n) = h[0]; *(f32x4*)(hc0 + (size_t)(u.pm * 2 + fr) * FF2 + FF + gcol + 4 * n) = h[1]; }
;                     f32x4 a;
; #pragma unroll
;                     for (int e = 0; e < 4; ++e) { const float g = h[0][e]; a[e] = g * __builtin_amdgcn_rcpf(1.0f + __builtin_amdgcn_exp2f(-1.4426950408889634f * g)) * h[1][e]; }
;                     const unsigned p0 = cvt_pk_bf16(a[0], a[1]), p1 = cvt_pk_bf16(a[2], a[3]);
;                     if (n == 0) { pk_lo[ai][m][0] = p0; pk_lo[ai][m][1] = p1; }
;                     else { u32x4 w; w.x = pk_lo[ai][m][0]; w.y = pk_lo[ai][m][1]; w.z = p0; w.w = p1;
;                         *(u32x4*)(act + (size_t)(u.pm * BM + ai * HALF + wr * 64 + m * 16 + fr) * FF + gcol) = w; }
;                     pg[0] = cur[0]; pg[1] = cur[1];
	v_pk_fma_f32 v[220:221], v[132:133], v[188:189], v[220:221]
	v_pk_fma_f32 v[222:223], v[134:135], v[196:197], v[222:223]
	v_pk_fma_f32 v[220:221], v[128:129], v[200:201], v[220:221]
	v_pk_fma_f32 v[222:223], v[130:131], v[204:205], v[222:223]
	s_mov_b64 exec, s[42:43]
	ds_read_b64 v[188:189], v235 offset:8192
	ds_read_b64 v[196:197], v235 offset:8200
	ds_read_b64 v[200:201], v237 offset:8192
	ds_read_b64 v[204:205], v237 offset:8200
	s_mov_b64 exec, -1
	ds_write_b128 v212, v[96:99] offset:8192
	s_mov_b64 exec, s[44:45]
	ds_read_b64 v[188:189], v235 offset:8192
	ds_read_b64 v[196:197], v235 offset:8200
	s_mov_b64 exec, s[82:83]
	ds_read_b64 v[200:201], v237 offset:8192
	ds_read_b64 v[204:205], v237 offset:8200
	s_mov_b64 exec, -1
	s_waitcnt lgkmcnt(0)
	v_pk_fma_f32 v[224:225], v[148:149], v[188:189], v[224:225]
	v_pk_fma_f32 v[226:227], v[150:151], v[196:197], v[226:227]
	v_pk_fma_f32 v[224:225], v[144:145], v[200:201], v[224:225]
	v_pk_fma_f32 v[226:227], v[146:147], v[204:205], v[226:227]
	v_pk_mul_f32 v[190:191], v[220:221], s[100:101] op_sel_hi:[1,0]
	v_pk_mul_f32 v[250:251], v[222:223], s[100:101] op_sel_hi:[1,0]
	v_exp_f32_e32 v190, v190
	v_exp_f32_e32 v191, v191
	v_exp_f32_e32 v250, v250
	v_exp_f32_e32 v251, v251
	v_pk_mul_f32 v[220:221], v[220:221], v[224:225]
	v_pk_mul_f32 v[222:223], v[222:223], v[226:227]
	v_pk_add_f32 v[190:191], v[190:191], 1.0 op_sel_hi:[1,0]
	v_pk_add_f32 v[250:251], v[250:251], 1.0 op_sel_hi:[1,0]
	v_rcp_f32_e32 v190, v190
	v_rcp_f32_e32 v191, v191
	v_rcp_f32_e32 v250, v250
	v_rcp_f32_e32 v251, v251
	v_pk_mul_f32 v[220:221], v[220:221], v[190:191]
	v_pk_mul_f32 v[222:223], v[222:223], v[250:251]
	v_cvt_pk_bf16_f32 v202, v220, v221
	v_cvt_pk_bf16_f32 v203, v222, v223
	global_load_dwordx4 v[124:127], v233, s[14:15] offset:16
	global_load_dwordx4 v[116:119], v233, s[16:17] offset:16
	global_load_dwordx4 v[108:111], v233, s[92:93] offset:16
	global_load_dwordx4 v[100:103], v233, s[60:61] offset:16
	v_add_u32_e32 v243, 0x2c00, v233
	global_load_dwordx4 v[120:123], v243, s[14:15] offset:16
	global_load_dwordx4 v[112:115], v243, s[16:17] offset:16
	global_load_dwordx4 v[104:107], v243, s[92:93] offset:16
	global_load_dwordx4 v[96:99], v243, s[60:61] offset:16
	v_pk_fma_f32 v[220:221], v[136:137], v[92:93], v[140:141]
	v_pk_fma_f32 v[222:223], v[138:139], v[94:95], v[142:143]
	v_pk_fma_f32 v[224:225], v[152:153], v[88:89], v[156:157]
	v_pk_fma_f32 v[226:227], v[154:155], v[90:91], v[158:159]
	s_andn2_b64 exec, exec, s[40:41]
	ds_write_b128 v212, v[178:181]
	ds_write_b128 v212, v[182:185] offset:8192
	s_mov_b64 exec, -1
	s_mov_b64 exec, s[42:43]
	ds_read_b64 v[188:189], v235
	ds_read_b64 v[196:197], v235 offset:8
	ds_read_b64 v[200:201], v237
	ds_read_b64 v[204:205], v237 offset:8
	s_mov_b64 exec, -1
	ds_write_b128 v212, v[92:95]
	s_mov_b64 exec, s[44:45]
	ds_read_b64 v[188:189], v235
	ds_read_b64 v[196:197], v235 offset:8
	s_mov_b64 exec, s[82:83]
	ds_read_b64 v[200:201], v237
	ds_read_b64 v[204:205], v237 offset:8
	s_mov_b64 exec, -1
	s_waitcnt lgkmcnt(0)
	v_pk_fma_f32 v[220:221], v[132:133], v[188:189], v[220:221]
	v_pk_fma_f32 v[222:223], v[134:135], v[196:197], v[222:223]
	v_pk_fma_f32 v[220:221], v[128:129], v[200:201], v[220:221]
	v_pk_fma_f32 v[222:223], v[130:131], v[204:205], v[222:223]
	s_mov_b64 exec, s[42:43]
	ds_read_b64 v[188:189], v235 offset:8192
	ds_read_b64 v[196:197], v235 offset:8200
	ds_read_b64 v[200:201], v237 offset:8192
	ds_read_b64 v[204:205], v237 offset:8200
	s_mov_b64 exec, -1
	ds_write_b128 v212, v[88:91] offset:8192
	s_mov_b64 exec, s[44:45]
	ds_read_b64 v[188:189], v235 offset:8192
	ds_read_b64 v[196:197], v235 offset:8200
	s_mov_b64 exec, s[82:83]
	ds_read_b64 v[200:201], v237 offset:8192
	ds_read_b64 v[204:205], v237 offset:8200
	s_mov_b64 exec, -1
	s_waitcnt lgkmcnt(0)
	v_pk_fma_f32 v[224:225], v[148:149], v[188:189], v[224:225]
	v_pk_fma_f32 v[226:227], v[150:151], v[196:197], v[226:227]
	v_pk_fma_f32 v[224:225], v[144:145], v[200:201], v[224:225]
	v_pk_fma_f32 v[226:227], v[146:147], v[204:205], v[226:227]
	v_pk_mul_f32 v[190:191], v[220:221], s[100:101] op_sel_hi:[1,0]
	v_pk_mul_f32 v[250:251], v[222:223], s[100:101] op_sel_hi:[1,0]
	v_exp_f32_e32 v190, v190
	v_exp_f32_e32 v191, v191
	v_exp_f32_e32 v250, v250
	v_exp_f32_e32 v251, v251
	v_pk_mul_f32 v[220:221], v[220:221], v[224:225]
	v_pk_mul_f32 v[222:223], v[222:223], v[226:227]
	v_pk_add_f32 v[190:191], v[190:191], 1.0 op_sel_hi:[1,0]
	v_pk_add_f32 v[250:251], v[250:251], 1.0 op_sel_hi:[1,0]
	v_rcp_f32_e32 v190, v190
	v_rcp_f32_e32 v191, v191
	v_rcp_f32_e32 v250, v250
	v_rcp_f32_e32 v251, v251
	v_pk_mul_f32 v[220:221], v[220:221], v[190:191]
	v_pk_mul_f32 v[222:223], v[222:223], v[250:251]
	v_cvt_pk_bf16_f32 v160, v220, v221
	v_cvt_pk_bf16_f32 v161, v222, v223
	v_pk_fma_f32 v[220:221], v[136:137], v[84:85], v[140:141]
	v_pk_fma_f32 v[222:223], v[138:139], v[86:87], v[142:143]
	v_pk_fma_f32 v[224:225], v[152:153], v[80:81], v[156:157]
	v_pk_fma_f32 v[226:227], v[154:155], v[82:83], v[158:159]
	s_mov_b64 exec, s[42:43]
	ds_read_b64 v[188:189], v235
	ds_read_b64 v[196:197], v235 offset:8
	ds_read_b64 v[200:201], v237
	ds_read_b64 v[204:205], v237 offset:8
	s_mov_b64 exec, -1
	ds_write_b128 v212, v[84:87]
	s_mov_b64 exec, s[44:45]
	ds_read_b64 v[188:189], v235
	ds_read_b64 v[196:197], v235 offset:8
	s_mov_b64 exec, s[82:83]
	ds_read_b64 v[200:201], v237
	ds_read_b64 v[204:205], v237 offset:8
	s_mov_b64 exec, -1
	s_waitcnt lgkmcnt(0)
; #define PG8_LAS __attribute__((address_space(3)))
; __device__ __forceinline__ unsigned cvt_pk_bf16(float lo, float hi) { unsigned r; asm volatile("v_cvt_pk_bf16_f32 %0, %1, %2" : "=v"(r) : "v"(lo), "v"(hi)); return r; }
;     __device__ __forceinline__ void operator()(const f32x4 (&acc)[2][2][4][2], const Unit& u, int wr, int wc, int fr, int fq) const {
;     ...
;             for (int ai = 0; ai < 2; ++ai) {
;                 f32x4 pg[2]; const int pb = ai * 2 + wr - 1;
; #pragma unroll
;                 for (int bj = 0; bj < 2; ++bj) { pg[bj] = (f32x4){0.f, 0.f, 0.f, 0.f};
;                     if (pb >= 0 && fr >= 14) pg[bj] = *(const PG8_LAS f32x4*)(halo + (pb * 2 + (fr - 14)) * 256 + bj * HALF + lcol + 4 * n); }
; #pragma unroll
;                 for (int m = 0; m < 4; ++m) {
;                     f32x4 cur[2], h[2];
; #pragma unroll
;                     for (int bj = 0; bj < 2; ++bj) { cur[bj] = acc[ai][bj][m][n] * rs[ai][m]; f32x4 x1, x2;
; #pragma unroll
;                         for (int e = 0; e < 4; ++e) { const float c1 = dpp_ror1(cur[bj][e]), p1 = dpp_ror1(pg[bj][e]), c2 = dpp_ror2(cur[bj][e]), p2 = dpp_ror2(pg[bj][e]);
;                             x1[e] = fr >= 1 ? c1 : p1; x2[e] = fr >= 2 ? c2 : p2; }
;                         h[bj] = bb[bj] + w0[bj] * x2 + w1[bj] * x1 + w2[bj] * cur[bj]; }
;                     if (ai == 0 && wr == 0 && m == 0 && fr < 2) {
;                         *(f32x4*)(hc0 + (size_t)(u.pm * 2 + fr) * FF2 + gcol + 4 * n) = h[0]; *(f32x4*)(hc0 + (size_t)(u.pm * 2 + fr) * FF2 + FF + gcol + 4 * n) = h[1]; }
;                     f32x4 a;
; #pragma unroll
;                     for (int e = 0; e < 4; ++e) { const float g = h[0][e]; a[e] = g * __builtin_amdgcn_rcpf(1.0f + __builtin_amdgcn_exp2f(-1.4426950408889634f * g)) * h[1][e]; }
;                     const unsigned p0 = cvt_pk_bf16(a[0], a[1]), p1 = cvt_pk_bf16(a[2], a[3]);
;                     if (n == 0) { pk_lo[ai][m][0] = p0; pk_lo[ai][m][1] = p1; }
;                     else { u32x4 w; w.x = pk_lo[ai][m][0]; w.y = pk_lo[ai][m][1]; w.z = p0; w.w = p1;
;                         *(u32x4*)(act + (size_t)(u.pm * BM + ai * HALF + wr * 64 + m * 16 + fr) * FF + gcol) = w; }
;                     pg[0] = cur[0]; pg[1] = cur[1];
	v_pk_fma_f32 v[220:221], v[132:133], v[188:189], v[220:221]
	v_pk_fma_f32 v[222:223], v[134:135], v[196:197], v[222:223]
	v_pk_fma_f32 v[220:221], v[128:129], v[200:201], v[220:221]
	v_pk_fma_f32 v[222:223], v[130:131], v[204:205], v[222:223]
	s_mov_b64 exec, s[42:43]
	ds_read_b64 v[188:189], v235 offset:8192
	ds_read_b64 v[196:197], v235 offset:8200
	ds_read_b64 v[200:201], v237 offset:8192
	ds_read_b64 v[204:205], v237 offset:8200
	s_mov_b64 exec, -1
	ds_write_b128 v212, v[80:83] offset:8192
	s_mov_b64 exec, s[44:45]
	ds_read_b64 v[188:189], v235 offset:8192
	ds_read_b64 v[196:197], v235 offset:8200
	s_mov_b64 exec, s[82:83]
	ds_read_b64 v[200:201], v237 offset:8192
	ds_read_b64 v[204:205], v237 offset:8200
	s_mov_b64 exec, -1
	s_waitcnt lgkmcnt(0)
	v_pk_fma_f32 v[224:225], v[148:149], v[188:189], v[224:225]
	v_pk_fma_f32 v[226:227], v[150:151], v[196:197], v[226:227]
	v_pk_fma_f32 v[224:225], v[144:145], v[200:201], v[224:225]
	v_pk_fma_f32 v[226:227], v[146:147], v[204:205], v[226:227]
	v_pk_mul_f32 v[190:191], v[220:221], s[100:101] op_sel_hi:[1,0]
	v_pk_mul_f32 v[250:251], v[222:223], s[100:101] op_sel_hi:[1,0]
	v_exp_f32_e32 v190, v190
	v_exp_f32_e32 v191, v191
	v_exp_f32_e32 v250, v250
	v_exp_f32_e32 v251, v251
	v_pk_mul_f32 v[220:221], v[220:221], v[224:225]
	v_pk_mul_f32 v[222:223], v[222:223], v[226:227]
	v_pk_add_f32 v[190:191], v[190:191], 1.0 op_sel_hi:[1,0]
	v_pk_add_f32 v[250:251], v[250:251], 1.0 op_sel_hi:[1,0]
	v_rcp_f32_e32 v190, v190
	v_rcp_f32_e32 v191, v191
	v_rcp_f32_e32 v250, v250
	v_rcp_f32_e32 v251, v251
	v_pk_mul_f32 v[220:221], v[220:221], v[190:191]
	v_pk_mul_f32 v[222:223], v[222:223], v[250:251]
	v_cvt_pk_bf16_f32 v164, v220, v221
	v_cvt_pk_bf16_f32 v165, v222, v223
	v_pk_fma_f32 v[220:221], v[136:137], v[76:77], v[140:141]
	v_pk_fma_f32 v[222:223], v[138:139], v[78:79], v[142:143]
	v_pk_fma_f32 v[224:225], v[152:153], v[72:73], v[156:157]
	v_pk_fma_f32 v[226:227], v[154:155], v[74:75], v[158:159]
	s_mov_b64 exec, s[42:43]
	ds_read_b64 v[188:189], v235
	ds_read_b64 v[196:197], v235 offset:8
	ds_read_b64 v[200:201], v237
	ds_read_b64 v[204:205], v237 offset:8
	s_mov_b64 exec, -1
	ds_write_b128 v212, v[76:79]
	s_mov_b64 exec, s[44:45]
	ds_read_b64 v[188:189], v235
	ds_read_b64 v[196:197], v235 offset:8
	s_mov_b64 exec, s[82:83]
	ds_read_b64 v[200:201], v237
	ds_read_b64 v[204:205], v237 offset:8
	s_mov_b64 exec, -1
	s_waitcnt lgkmcnt(0)
	v_pk_fma_f32 v[220:221], v[132:133], v[188:189], v[220:221]
	v_pk_fma_f32 v[222:223], v[134:135], v[196:197], v[222:223]
	v_pk_fma_f32 v[220:221], v[128:129], v[200:201], v[220:221]
	v_pk_fma_f32 v[222:223], v[130:131], v[204:205], v[222:223]
	s_mov_b64 exec, s[42:43]
	ds_read_b64 v[188:189], v235 offset:8192
	ds_read_b64 v[196:197], v235 offset:8200
	ds_read_b64 v[200:201], v237 offset:8192
	ds_read_b64 v[204:205], v237 offset:8200
	s_mov_b64 exec, -1
	ds_write_b128 v212, v[72:75] offset:8192
	s_mov_b64 exec, s[44:45]
	ds_read_b64 v[188:189], v235 offset:8192
	ds_read_b64 v[196:197], v235 offset:8200
	s_mov_b64 exec, s[82:83]
	ds_read_b64 v[200:201], v237 offset:8192
	ds_read_b64 v[204:205], v237 offset:8200
	s_mov_b64 exec, -1
	s_waitcnt lgkmcnt(0)
	v_pk_fma_f32 v[224:225], v[148:149], v[188:189], v[224:225]
	v_pk_fma_f32 v[226:227], v[150:151], v[196:197], v[226:227]
	v_pk_fma_f32 v[224:225], v[144:145], v[200:201], v[224:225]
	v_pk_fma_f32 v[226:227], v[146:147], v[204:205], v[226:227]
	v_pk_mul_f32 v[190:191], v[220:221], s[100:101] op_sel_hi:[1,0]
	v_pk_mul_f32 v[250:251], v[222:223], s[100:101] op_sel_hi:[1,0]
	v_exp_f32_e32 v190, v190
	v_exp_f32_e32 v191, v191
	v_exp_f32_e32 v250, v250
	v_exp_f32_e32 v251, v251
	v_pk_mul_f32 v[220:221], v[220:221], v[224:225]
	v_pk_mul_f32 v[222:223], v[222:223], v[226:227]
	v_pk_add_f32 v[190:191], v[190:191], 1.0 op_sel_hi:[1,0]
	v_pk_add_f32 v[250:251], v[250:251], 1.0 op_sel_hi:[1,0]
	v_rcp_f32_e32 v190, v190
	v_rcp_f32_e32 v191, v191
	v_rcp_f32_e32 v250, v250
	v_rcp_f32_e32 v251, v251
	v_pk_mul_f32 v[220:221], v[220:221], v[190:191]
	v_pk_mul_f32 v[222:223], v[222:223], v[250:251]
	v_cvt_pk_bf16_f32 v178, v220, v221
	v_cvt_pk_bf16_f32 v179, v222, v223
	s_and_b64 vcc, exec, s[94:95]
	s_cbranch_vccnz .Lp7_hz1
	ds_read_b128 v[92:95], v215
	ds_read_b128 v[88:91], v216
	s_branch .Lp7_hr1

; #define PG8_LAS __attribute__((address_space(3)))
; __device__ __forceinline__ unsigned cvt_pk_bf16(float lo, float hi) { unsigned r; asm volatile("v_cvt_pk_bf16_f32 %0, %1, %2" : "=v"(r) : "v"(lo), "v"(hi)); return r; }
;     __device__ __forceinline__ void operator()(const f32x4 (&acc)[2][2][4][2], const Unit& u, int wr, int wc, int fr, int fq) const {
;     ...
;             for (int ai = 0; ai < 2; ++ai) {
;                 f32x4 pg[2]; const int pb = ai * 2 + wr - 1;
; #pragma unroll
;                 for (int bj = 0; bj < 2; ++bj) { pg[bj] = (f32x4){0.f, 0.f, 0.f, 0.f};
;                     if (pb >= 0 && fr >= 14) pg[bj] = *(const PG8_LAS f32x4*)(halo + (pb * 2 + (fr - 14)) * 256 + bj * HALF + lcol + 4 * n); }
; #pragma unroll
;                 for (int m = 0; m < 4; ++m) {
;                     f32x4 cur[2], h[2];
; #pragma unroll
;                     for (int bj = 0; bj < 2; ++bj) { cur[bj] = acc[ai][bj][m][n] * rs[ai][m]; f32x4 x1, x2;
; #pragma unroll
;                         for (int e = 0; e < 4; ++e) { const float c1 = dpp_ror1(cur[bj][e]), p1 = dpp_ror1(pg[bj][e]), c2 = dpp_ror2(cur[bj][e]), p2 = dpp_ror2(pg[bj][e]);
;                             x1[e] = fr >= 1 ? c1 : p1; x2[e] = fr >= 2 ? c2 : p2; }
;                         h[bj] = bb[bj] + w0[bj] * x2 + w1[bj] * x1 + w2[bj] * cur[bj]; }
;                     if (ai == 0 && wr == 0 && m == 0 && fr < 2) {
;                         *(f32x4*)(hc0 + (size_t)(u.pm * 2 + fr) * FF2 + gcol + 4 * n) = h[0]; *(f32x4*)(hc0 + (size_t)(u.pm * 2 + fr) * FF2 + FF + gcol + 4 * n) = h[1]; }
;                     f32x4 a;
; #pragma unroll
;                     for (int e = 0; e < 4; ++e) { const float g = h[0][e]; a[e] = g * __builtin_amdgcn_rcpf(1.0f + __builtin_amdgcn_exp2f(-1.4426950408889634f * g)) * h[1][e]; }
;                     const unsigned p0 = cvt_pk_bf16(a[0], a[1]), p1 = cvt_pk_bf16(a[2], a[3]);
;                     if (n == 0) { pk_lo[ai][m][0] = p0; pk_lo[ai][m][1] = p1; }
;                     else { u32x4 w; w.x = pk_lo[ai][m][0]; w.y = pk_lo[ai][m][1]; w.z = p0; w.w = p1;
;                         *(u32x4*)(act + (size_t)(u.pm * BM + ai * HALF + wr * 64 + m * 16 + fr) * FF + gcol) = w; }
;                     pg[0] = cur[0]; pg[1] = cur[1];
.Lp7_hr1:
	ds_read_b128 v[84:87], v217
	ds_read_b128 v[80:83], v218
	v_pk_fma_f32 v[220:221], v[136:137], v[68:69], v[140:141]
	v_pk_fma_f32 v[222:223], v[138:139], v[70:71], v[142:143]
	v_pk_fma_f32 v[224:225], v[152:153], v[64:65], v[156:157]
	v_pk_fma_f32 v[226:227], v[154:155], v[66:67], v[158:159]
	s_mov_b64 exec, s[42:43]
	ds_read_b64 v[188:189], v235
	ds_read_b64 v[196:197], v235 offset:8
	ds_read_b64 v[200:201], v237
	ds_read_b64 v[204:205], v237 offset:8
	s_mov_b64 exec, -1
	ds_write_b128 v212, v[68:71]
	s_mov_b64 exec, s[44:45]
	ds_read_b64 v[188:189], v235
	ds_read_b64 v[196:197], v235 offset:8
	s_mov_b64 exec, s[82:83]
	ds_read_b64 v[200:201], v237
	ds_read_b64 v[204:205], v237 offset:8
	s_mov_b64 exec, -1
	s_waitcnt lgkmcnt(0)
	v_pk_fma_f32 v[220:221], v[132:133], v[188:189], v[220:221]
	v_pk_fma_f32 v[222:223], v[134:135], v[196:197], v[222:223]
	v_pk_fma_f32 v[220:221], v[128:129], v[200:201], v[220:221]
	v_pk_fma_f32 v[222:223], v[130:131], v[204:205], v[222:223]
	s_mov_b64 exec, s[42:43]
	ds_read_b64 v[188:189], v235 offset:8192
	ds_read_b64 v[196:197], v235 offset:8200
	ds_read_b64 v[200:201], v237 offset:8192
	ds_read_b64 v[204:205], v237 offset:8200
	s_mov_b64 exec, -1
	ds_write_b128 v212, v[64:67] offset:8192
	s_mov_b64 exec, s[44:45]
	ds_read_b64 v[188:189], v235 offset:8192
	ds_read_b64 v[196:197], v235 offset:8200
	s_mov_b64 exec, s[82:83]
	ds_read_b64 v[200:201], v237 offset:8192
	ds_read_b64 v[204:205], v237 offset:8200
	s_mov_b64 exec, -1
	s_waitcnt lgkmcnt(0)
	v_pk_fma_f32 v[224:225], v[148:149], v[188:189], v[224:225]
	v_pk_fma_f32 v[226:227], v[150:151], v[196:197], v[226:227]
	v_pk_fma_f32 v[224:225], v[144:145], v[200:201], v[224:225]
	v_pk_fma_f32 v[226:227], v[146:147], v[204:205], v[226:227]
	v_pk_mul_f32 v[190:191], v[220:221], s[100:101] op_sel_hi:[1,0]
	v_pk_mul_f32 v[250:251], v[222:223], s[100:101] op_sel_hi:[1,0]
	v_exp_f32_e32 v190, v190
	v_exp_f32_e32 v191, v191
	v_exp_f32_e32 v250, v250
	v_exp_f32_e32 v251, v251
	v_pk_mul_f32 v[220:221], v[220:221], v[224:225]
	v_pk_mul_f32 v[222:223], v[222:223], v[226:227]
	v_pk_add_f32 v[190:191], v[190:191], 1.0 op_sel_hi:[1,0]
	v_pk_add_f32 v[250:251], v[250:251], 1.0 op_sel_hi:[1,0]
	v_rcp_f32_e32 v190, v190
	v_rcp_f32_e32 v191, v191
	v_rcp_f32_e32 v250, v250
	v_rcp_f32_e32 v251, v251
	v_pk_mul_f32 v[220:221], v[220:221], v[190:191]
	v_pk_mul_f32 v[222:223], v[222:223], v[250:251]
	v_cvt_pk_bf16_f32 v182, v220, v221
	v_cvt_pk_bf16_f32 v183, v222, v223
	s_waitcnt vmcnt(0) lgkmcnt(0)
	v_pk_fma_f32 v[220:221], v[108:109], v[60:61], v[100:101]
	v_pk_fma_f32 v[222:223], v[110:111], v[62:63], v[102:103]
	v_pk_fma_f32 v[224:225], v[104:105], v[56:57], v[96:97]
	v_pk_fma_f32 v[226:227], v[106:107], v[58:59], v[98:99]
	s_andn2_b64 exec, exec, s[40:41]
	ds_write_b128 v212, v[92:95]
	ds_write_b128 v212, v[88:91] offset:8192
	s_mov_b64 exec, -1
	s_mov_b64 exec, s[42:43]
	ds_read_b64 v[72:73], v235
	ds_read_b64 v[74:75], v235 offset:8
	ds_read_b64 v[76:77], v237
	ds_read_b64 v[78:79], v237 offset:8
	s_mov_b64 exec, -1
	ds_write_b128 v212, v[60:63]
	s_mov_b64 exec, s[44:45]
	ds_read_b64 v[72:73], v235
	ds_read_b64 v[74:75], v235 offset:8
	s_mov_b64 exec, s[82:83]
	ds_read_b64 v[76:77], v237
	ds_read_b64 v[78:79], v237 offset:8
	s_mov_b64 exec, -1
	s_waitcnt lgkmcnt(0)
	v_pk_fma_f32 v[220:221], v[116:117], v[72:73], v[220:221]
	v_pk_fma_f32 v[222:223], v[118:119], v[74:75], v[222:223]
	v_pk_fma_f32 v[220:221], v[124:125], v[76:77], v[220:221]
	v_pk_fma_f32 v[222:223], v[126:127], v[78:79], v[222:223]
	s_mov_b64 exec, s[42:43]
	ds_read_b64 v[72:73], v235 offset:8192
	ds_read_b64 v[74:75], v235 offset:8200
	ds_read_b64 v[76:77], v237 offset:8192
	ds_read_b64 v[78:79], v237 offset:8200
	s_mov_b64 exec, -1
	ds_write_b128 v212, v[56:59] offset:8192
	s_mov_b64 exec, s[44:45]
	ds_read_b64 v[72:73], v235 offset:8192
	ds_read_b64 v[74:75], v235 offset:8200
	s_mov_b64 exec, s[82:83]
	ds_read_b64 v[76:77], v237 offset:8192
	ds_read_b64 v[78:79], v237 offset:8200
	s_mov_b64 exec, -1
	s_waitcnt lgkmcnt(0)
	v_pk_fma_f32 v[224:225], v[112:113], v[72:73], v[224:225]
	v_pk_fma_f32 v[226:227], v[114:115], v[74:75], v[226:227]
	v_pk_fma_f32 v[224:225], v[120:121], v[76:77], v[224:225]
	v_pk_fma_f32 v[226:227], v[122:123], v[78:79], v[226:227]
	s_and_saveexec_b64 s[0:1], s[12:13]
	global_store_dwordx4 v241, v[220:223], s[84:85] offset:16
	global_store_dwordx4 v249, v[224:227], s[84:85] offset:16
	s_or_b64 exec, exec, s[0:1]
	v_pk_mul_f32 v[190:191], v[220:221], s[100:101] op_sel_hi:[1,0]
	v_pk_mul_f32 v[250:251], v[222:223], s[100:101] op_sel_hi:[1,0]
	v_exp_f32_e32 v190, v190
	v_exp_f32_e32 v191, v191
	v_exp_f32_e32 v250, v250
	v_exp_f32_e32 v251, v251
	v_pk_mul_f32 v[220:221], v[220:221], v[224:225]
	v_pk_mul_f32 v[222:223], v[222:223], v[226:227]
	v_pk_add_f32 v[190:191], v[190:191], 1.0 op_sel_hi:[1,0]
	v_pk_add_f32 v[250:251], v[250:251], 1.0 op_sel_hi:[1,0]
	v_rcp_f32_e32 v190, v190
	v_rcp_f32_e32 v191, v191
	v_rcp_f32_e32 v250, v250
	v_rcp_f32_e32 v251, v251
	v_pk_mul_f32 v[220:221], v[220:221], v[190:191]
	v_pk_mul_f32 v[222:223], v[222:223], v[250:251]
	v_cvt_pk_bf16_f32 v188, v220, v221
	v_cvt_pk_bf16_f32 v189, v222, v223
	global_store_dwordx4 v239, v[186:189], s[24:25]
	v_pk_fma_f32 v[220:221], v[108:109], v[52:53], v[100:101]
	v_pk_fma_f32 v[222:223], v[110:111], v[54:55], v[102:103]
	v_pk_fma_f32 v[224:225], v[104:105], v[48:49], v[96:97]
	v_pk_fma_f32 v[226:227], v[106:107], v[50:51], v[98:99]
	s_mov_b64 exec, s[42:43]
	ds_read_b64 v[72:73], v235
	ds_read_b64 v[74:75], v235 offset:8
	ds_read_b64 v[76:77], v237
	ds_read_b64 v[78:79], v237 offset:8
	s_mov_b64 exec, -1
	ds_write_b128 v212, v[52:55]
	s_mov_b64 exec, s[44:45]
	ds_read_b64 v[72:73], v235
	ds_read_b64 v[74:75], v235 offset:8
	s_mov_b64 exec, s[82:83]
	ds_read_b64 v[76:77], v237
	ds_read_b64 v[78:79], v237 offset:8
	s_mov_b64 exec, -1
	s_waitcnt lgkmcnt(0)
; __device__ __forceinline__ unsigned cvt_pk_bf16(float lo, float hi) { unsigned r; asm volatile("v_cvt_pk_bf16_f32 %0, %1, %2" : "=v"(r) : "v"(lo), "v"(hi)); return r; }
; __device__ __forceinline__ float dpp_ror1(float x) { return __int_as_float(__builtin_amdgcn_update_dpp(0, __float_as_int(x), 0x121, 0xf, 0xf, false)); }
; __device__ __forceinline__ float dpp_ror2(float x) { return __int_as_float(__builtin_amdgcn_update_dpp(0, __float_as_int(x), 0x122, 0xf, 0xf, false)); }
;     __device__ __forceinline__ void operator()(const f32x4 (&acc)[2][2][4][2], const Unit& u, int wr, int wc, int fr, int fq) const {
;     ...
;                 for (int m = 0; m < 4; ++m) {
;                     f32x4 cur[2], h[2];
; #pragma unroll
;                     for (int bj = 0; bj < 2; ++bj) { cur[bj] = acc[ai][bj][m][n] * rs[ai][m]; f32x4 x1, x2;
; #pragma unroll
;                         for (int e = 0; e < 4; ++e) { const float c1 = dpp_ror1(cur[bj][e]), p1 = dpp_ror1(pg[bj][e]), c2 = dpp_ror2(cur[bj][e]), p2 = dpp_ror2(pg[bj][e]);
;                             x1[e] = fr >= 1 ? c1 : p1; x2[e] = fr >= 2 ? c2 : p2; }
;                         h[bj] = bb[bj] + w0[bj] * x2 + w1[bj] * x1 + w2[bj] * cur[bj]; }
;                     if (ai == 0 && wr == 0 && m == 0 && fr < 2) {
;                         *(f32x4*)(hc0 + (size_t)(u.pm * 2 + fr) * FF2 + gcol + 4 * n) = h[0]; *(f32x4*)(hc0 + (size_t)(u.pm * 2 + fr) * FF2 + FF + gcol + 4 * n) = h[1]; }
;                     f32x4 a;
; #pragma unroll
;                     for (int e = 0; e < 4; ++e) { const float g = h[0][e]; a[e] = g * __builtin_amdgcn_rcpf(1.0f + __builtin_amdgcn_exp2f(-1.4426950408889634f * g)) * h[1][e]; }
;                     const unsigned p0 = cvt_pk_bf16(a[0], a[1]), p1 = cvt_pk_bf16(a[2], a[3]);
;                     if (n == 0) { pk_lo[ai][m][0] = p0; pk_lo[ai][m][1] = p1; }
;                     else { u32x4 w; w.x = pk_lo[ai][m][0]; w.y = pk_lo[ai][m][1]; w.z = p0; w.w = p1;
;                         *(u32x4*)(act + (size_t)(u.pm * BM + ai * HALF + wr * 64 + m * 16 + fr) * FF + gcol) = w; }
;                     pg[0] = cur[0]; pg[1] = cur[1];
	v_pk_fma_f32 v[220:221], v[116:117], v[72:73], v[220:221]
	v_pk_fma_f32 v[222:223], v[118:119], v[74:75], v[222:223]
	v_pk_fma_f32 v[220:221], v[124:125], v[76:77], v[220:221]
	v_pk_fma_f32 v[222:223], v[126:127], v[78:79], v[222:223]
	s_mov_b64 exec, s[42:43]
	ds_read_b64 v[72:73], v235 offset:8192
	ds_read_b64 v[74:75], v235 offset:8200
	ds_read_b64 v[76:77], v237 offset:8192
	ds_read_b64 v[78:79], v237 offset:8200
	s_mov_b64 exec, -1
	ds_write_b128 v212, v[48:51] offset:8192
	s_mov_b64 exec, s[44:45]
	ds_read_b64 v[72:73], v235 offset:8192
	ds_read_b64 v[74:75], v235 offset:8200
	s_mov_b64 exec, s[82:83]
	ds_read_b64 v[76:77], v237 offset:8192
	ds_read_b64 v[78:79], v237 offset:8200
	s_mov_b64 exec, -1
	s_waitcnt lgkmcnt(0)
	v_pk_fma_f32 v[224:225], v[112:113], v[72:73], v[224:225]
	v_pk_fma_f32 v[226:227], v[114:115], v[74:75], v[226:227]
	v_pk_fma_f32 v[224:225], v[120:121], v[76:77], v[224:225]
	v_pk_fma_f32 v[226:227], v[122:123], v[78:79], v[226:227]
	v_pk_mul_f32 v[190:191], v[220:221], s[100:101] op_sel_hi:[1,0]
	v_pk_mul_f32 v[250:251], v[222:223], s[100:101] op_sel_hi:[1,0]
	v_exp_f32_e32 v190, v190
	v_exp_f32_e32 v191, v191
	v_exp_f32_e32 v250, v250
	v_exp_f32_e32 v251, v251
	v_pk_mul_f32 v[220:221], v[220:221], v[224:225]
	v_pk_mul_f32 v[222:223], v[222:223], v[226:227]
	v_pk_add_f32 v[190:191], v[190:191], 1.0 op_sel_hi:[1,0]
	v_pk_add_f32 v[250:251], v[250:251], 1.0 op_sel_hi:[1,0]
	v_rcp_f32_e32 v190, v190
	v_rcp_f32_e32 v191, v191
	v_rcp_f32_e32 v250, v250
	v_rcp_f32_e32 v251, v251
	v_pk_mul_f32 v[220:221], v[220:221], v[190:191]
	v_pk_mul_f32 v[222:223], v[222:223], v[250:251]
	v_cvt_pk_bf16_f32 v196, v220, v221
	v_cvt_pk_bf16_f32 v197, v222, v223
	v_add_u32_e32 v243, 0x16000, v239
	global_store_dwordx4 v243, v[194:197], s[24:25]
	v_pk_fma_f32 v[220:221], v[108:109], v[44:45], v[100:101]
	v_pk_fma_f32 v[222:223], v[110:111], v[46:47], v[102:103]
	v_pk_fma_f32 v[224:225], v[104:105], v[40:41], v[96:97]
	v_pk_fma_f32 v[226:227], v[106:107], v[42:43], v[98:99]
	s_mov_b64 exec, s[42:43]
	ds_read_b64 v[72:73], v235
	ds_read_b64 v[74:75], v235 offset:8
	ds_read_b64 v[76:77], v237
	ds_read_b64 v[78:79], v237 offset:8
	s_mov_b64 exec, -1
	ds_write_b128 v212, v[44:47]
	s_mov_b64 exec, s[44:45]
	ds_read_b64 v[72:73], v235
	ds_read_b64 v[74:75], v235 offset:8
	s_mov_b64 exec, s[82:83]
	ds_read_b64 v[76:77], v237
	ds_read_b64 v[78:79], v237 offset:8
	s_mov_b64 exec, -1
	s_waitcnt lgkmcnt(0)
	v_pk_fma_f32 v[220:221], v[116:117], v[72:73], v[220:221]
	v_pk_fma_f32 v[222:223], v[118:119], v[74:75], v[222:223]
	v_pk_fma_f32 v[220:221], v[124:125], v[76:77], v[220:221]
	v_pk_fma_f32 v[222:223], v[126:127], v[78:79], v[222:223]
	s_mov_b64 exec, s[42:43]
	ds_read_b64 v[72:73], v235 offset:8192
	ds_read_b64 v[74:75], v235 offset:8200
	ds_read_b64 v[76:77], v237 offset:8192
	ds_read_b64 v[78:79], v237 offset:8200
	s_mov_b64 exec, -1
	ds_write_b128 v212, v[40:43] offset:8192
	s_mov_b64 exec, s[44:45]
	ds_read_b64 v[72:73], v235 offset:8192
	ds_read_b64 v[74:75], v235 offset:8200
	s_mov_b64 exec, s[82:83]
	ds_read_b64 v[76:77], v237 offset:8192
	ds_read_b64 v[78:79], v237 offset:8200
	s_mov_b64 exec, -1
	s_waitcnt lgkmcnt(0)
	v_pk_fma_f32 v[224:225], v[112:113], v[72:73], v[224:225]
	v_pk_fma_f32 v[226:227], v[114:115], v[74:75], v[226:227]
	v_pk_fma_f32 v[224:225], v[120:121], v[76:77], v[224:225]
	v_pk_fma_f32 v[226:227], v[122:123], v[78:79], v[226:227]
	v_pk_mul_f32 v[190:191], v[220:221], s[100:101] op_sel_hi:[1,0]
	v_pk_mul_f32 v[250:251], v[222:223], s[100:101] op_sel_hi:[1,0]
	v_exp_f32_e32 v190, v190
	v_exp_f32_e32 v191, v191
	v_exp_f32_e32 v250, v250
	v_exp_f32_e32 v251, v251
	v_pk_mul_f32 v[220:221], v[220:221], v[224:225]
	v_pk_mul_f32 v[222:223], v[222:223], v[226:227]
	v_pk_add_f32 v[190:191], v[190:191], 1.0 op_sel_hi:[1,0]
	v_pk_add_f32 v[250:251], v[250:251], 1.0 op_sel_hi:[1,0]
	v_rcp_f32_e32 v190, v190
	v_rcp_f32_e32 v191, v191
	v_rcp_f32_e32 v250, v250
	v_rcp_f32_e32 v251, v251
	v_pk_mul_f32 v[220:221], v[220:221], v[190:191]
	v_pk_mul_f32 v[222:223], v[222:223], v[250:251]
	v_cvt_pk_bf16_f32 v200, v220, v221
	v_cvt_pk_bf16_f32 v201, v222, v223
	v_add_u32_e32 v243, 0x2c000, v239
	global_store_dwordx4 v243, v[198:201], s[24:25]
	v_pk_fma_f32 v[220:221], v[108:109], v[36:37], v[100:101]
	v_pk_fma_f32 v[222:223], v[110:111], v[38:39], v[102:103]
	v_pk_fma_f32 v[224:225], v[104:105], v[32:33], v[96:97]
	v_pk_fma_f32 v[226:227], v[106:107], v[34:35], v[98:99]
	s_mov_b64 exec, s[42:43]
	ds_read_b64 v[72:73], v235
	ds_read_b64 v[74:75], v235 offset:8
	ds_read_b64 v[76:77], v237
	ds_read_b64 v[78:79], v237 offset:8
	s_mov_b64 exec, -1
	ds_write_b128 v212, v[36:39]
	s_mov_b64 exec, s[44:45]
	ds_read_b64 v[72:73], v235
	ds_read_b64 v[74:75], v235 offset:8
	s_mov_b64 exec, s[82:83]
	ds_read_b64 v[76:77], v237
	ds_read_b64 v[78:79], v237 offset:8
	s_mov_b64 exec, -1
	s_waitcnt lgkmcnt(0)
	v_pk_fma_f32 v[220:221], v[116:117], v[72:73], v[220:221]
	v_pk_fma_f32 v[222:223], v[118:119], v[74:75], v[222:223]
	v_pk_fma_f32 v[220:221], v[124:125], v[76:77], v[220:221]
	v_pk_fma_f32 v[222:223], v[126:127], v[78:79], v[222:223]
	s_mov_b64 exec, s[42:43]
	ds_read_b64 v[72:73], v235 offset:8192
	ds_read_b64 v[74:75], v235 offset:8200
	ds_read_b64 v[76:77], v237 offset:8192
	ds_read_b64 v[78:79], v237 offset:8200
	s_mov_b64 exec, -1
	ds_write_b128 v212, v[32:35] offset:8192
	s_mov_b64 exec, s[44:45]
	ds_read_b64 v[72:73], v235 offset:8192
	ds_read_b64 v[74:75], v235 offset:8200
	s_mov_b64 exec, s[82:83]
	ds_read_b64 v[76:77], v237 offset:8192
	ds_read_b64 v[78:79], v237 offset:8200
	s_mov_b64 exec, -1
	s_waitcnt lgkmcnt(0)
	v_pk_fma_f32 v[224:225], v[112:113], v[72:73], v[224:225]
	v_pk_fma_f32 v[226:227], v[114:115], v[74:75], v[226:227]
	v_pk_fma_f32 v[224:225], v[120:121], v[76:77], v[224:225]
	v_pk_fma_f32 v[226:227], v[122:123], v[78:79], v[226:227]
	v_pk_mul_f32 v[190:191], v[220:221], s[100:101] op_sel_hi:[1,0]
	v_pk_mul_f32 v[250:251], v[222:223], s[100:101] op_sel_hi:[1,0]
	v_exp_f32_e32 v190, v190
	v_exp_f32_e32 v191, v191
	v_exp_f32_e32 v250, v250
	v_exp_f32_e32 v251, v251
	v_pk_mul_f32 v[220:221], v[220:221], v[224:225]
	v_pk_mul_f32 v[222:223], v[222:223], v[226:227]
	v_pk_add_f32 v[190:191], v[190:191], 1.0 op_sel_hi:[1,0]
	v_pk_add_f32 v[250:251], v[250:251], 1.0 op_sel_hi:[1,0]
	v_rcp_f32_e32 v190, v190
	v_rcp_f32_e32 v191, v191
	v_rcp_f32_e32 v250, v250
	v_rcp_f32_e32 v251, v251
	v_pk_mul_f32 v[220:221], v[220:221], v[190:191]
	v_pk_mul_f32 v[222:223], v[222:223], v[250:251]
	v_cvt_pk_bf16_f32 v204, v220, v221
	v_cvt_pk_bf16_f32 v205, v222, v223
	v_add_u32_e32 v243, 0x42000, v239
	global_store_dwordx4 v243, v[202:205], s[24:25]
	s_and_b64 vcc, exec, s[46:47]
	s_cbranch_vccz .Lp7_nopf
; __device__ __forceinline__ unsigned cvt_pk_bf16(float lo, float hi) { unsigned r; asm volatile("v_cvt_pk_bf16_f32 %0, %1, %2" : "=v"(r) : "v"(lo), "v"(hi)); return r; }
; __device__ __forceinline__ float dpp_ror1(float x) { return __int_as_float(__builtin_amdgcn_update_dpp(0, __float_as_int(x), 0x121, 0xf, 0xf, false)); }
; __device__ __forceinline__ float row_rstd(const float* slots, int row) {
;     const f32x4* s = (const f32x4*)(slots + (size_t)row * 16);
;     const f32x4 a = s[0], b = s[1], c = s[2], d = s[3];
;     const f32x4 t = (a + b) + (c + d);
;     const float ss = (t[0] + t[1]) + (t[2] + t[3]);
;     return __builtin_amdgcn_rsqf(ss * (1.0f / 1024.0f) + 1e-6f);
;     __device__ __forceinline__ void operator()(const f32x4 (&acc)[2][2][4][2], const Unit& u, int wr, int wc, int fr, int fq) const {
;     ...
;                 for (int m = 0; m < 4; ++m) {
;                     f32x4 cur[2], h[2];
; #pragma unroll
;                     for (int bj = 0; bj < 2; ++bj) { cur[bj] = acc[ai][bj][m][n] * rs[ai][m]; f32x4 x1, x2;
; #pragma unroll
;                         for (int e = 0; e < 4; ++e) { const float c1 = dpp_ror1(cur[bj][e]), p1 = dpp_ror1(pg[bj][e]), c2 = dpp_ror2(cur[bj][e]), p2 = dpp_ror2(pg[bj][e]);
;                             x1[e] = fr >= 1 ? c1 : p1; x2[e] = fr >= 2 ? c2 : p2; }
;                         h[bj] = bb[bj] + w0[bj] * x2 + w1[bj] * x1 + w2[bj] * cur[bj]; }
;                     if (ai == 0 && wr == 0 && m == 0 && fr < 2) {
;                         *(f32x4*)(hc0 + (size_t)(u.pm * 2 + fr) * FF2 + gcol + 4 * n) = h[0]; *(f32x4*)(hc0 + (size_t)(u.pm * 2 + fr) * FF2 + FF + gcol + 4 * n) = h[1]; }
;                     f32x4 a;
; #pragma unroll
;                     for (int e = 0; e < 4; ++e) { const float g = h[0][e]; a[e] = g * __builtin_amdgcn_rcpf(1.0f + __builtin_amdgcn_exp2f(-1.4426950408889634f * g)) * h[1][e]; }
;                     const unsigned p0 = cvt_pk_bf16(a[0], a[1]), p1 = cvt_pk_bf16(a[2], a[3]);
;                     if (n == 0) { pk_lo[ai][m][0] = p0; pk_lo[ai][m][1] = p1; }
;                     else { u32x4 w; w.x = pk_lo[ai][m][0]; w.y = pk_lo[ai][m][1]; w.z = p0; w.w = p1;
;                         *(u32x4*)(act + (size_t)(u.pm * BM + ai * HALF + wr * 64 + m * 16 + fr) * FF + gcol) = w; }
	s_cmp_eq_u32 s10, s71
	s_cbranch_scc1 .Lp7_nopf
	s_lshl_b32 s78, s10, 8
	s_add_i32 s78, s78, s8
	s_mov_b32 s79, 1
	v_or_b32_e32 v229, s78, v209
	v_lshlrev_b32_e32 v229, 6, v229
	v_add_u32_e32 v231, 0x2000, v229
	global_load_dwordx4 v[60:63], v229, s[26:27]
	global_load_dwordx4 v[52:55], v229, s[26:27] offset:16
	global_load_dwordx4 v[44:47], v229, s[26:27] offset:32
	global_load_dwordx4 v[36:39], v229, s[26:27] offset:48
	global_load_dwordx4 v[56:59], v231, s[26:27]
	global_load_dwordx4 v[48:51], v231, s[26:27] offset:16
	global_load_dwordx4 v[40:43], v231, s[26:27] offset:32
	global_load_dwordx4 v[32:35], v231, s[26:27] offset:48
.Lp7_nopf:
	v_pk_fma_f32 v[220:221], v[108:109], v[28:29], v[100:101]
	v_pk_fma_f32 v[222:223], v[110:111], v[30:31], v[102:103]
	v_pk_fma_f32 v[224:225], v[104:105], v[24:25], v[96:97]
	v_pk_fma_f32 v[226:227], v[106:107], v[26:27], v[98:99]
	s_andn2_b64 exec, exec, s[40:41]
	ds_write_b128 v212, v[84:87]
	ds_write_b128 v212, v[80:83] offset:8192
	s_mov_b64 exec, -1
	s_mov_b64 exec, s[42:43]
	ds_read_b64 v[72:73], v235
	ds_read_b64 v[74:75], v235 offset:8
	ds_read_b64 v[76:77], v237
	ds_read_b64 v[78:79], v237 offset:8
	s_mov_b64 exec, -1
	ds_write_b128 v212, v[28:31]
	s_mov_b64 exec, s[44:45]
	ds_read_b64 v[72:73], v235
	ds_read_b64 v[74:75], v235 offset:8
	s_mov_b64 exec, s[82:83]
	ds_read_b64 v[76:77], v237
	ds_read_b64 v[78:79], v237 offset:8
	s_mov_b64 exec, -1
	s_waitcnt lgkmcnt(0)
	v_pk_fma_f32 v[220:221], v[116:117], v[72:73], v[220:221]
	v_pk_fma_f32 v[222:223], v[118:119], v[74:75], v[222:223]
	v_pk_fma_f32 v[220:221], v[124:125], v[76:77], v[220:221]
	v_pk_fma_f32 v[222:223], v[126:127], v[78:79], v[222:223]
	s_mov_b64 exec, s[42:43]
	ds_read_b64 v[72:73], v235 offset:8192
	ds_read_b64 v[74:75], v235 offset:8200
	ds_read_b64 v[76:77], v237 offset:8192
	ds_read_b64 v[78:79], v237 offset:8200
	s_mov_b64 exec, -1
	ds_write_b128 v212, v[24:27] offset:8192
	s_mov_b64 exec, s[44:45]
	ds_read_b64 v[72:73], v235 offset:8192
	ds_read_b64 v[74:75], v235 offset:8200
	s_mov_b64 exec, s[82:83]
	ds_read_b64 v[76:77], v237 offset:8192
	ds_read_b64 v[78:79], v237 offset:8200
	s_mov_b64 exec, -1
	s_waitcnt lgkmcnt(0)
	v_pk_fma_f32 v[224:225], v[112:113], v[72:73], v[224:225]
	v_pk_fma_f32 v[226:227], v[114:115], v[74:75], v[226:227]
	v_pk_fma_f32 v[224:225], v[120:121], v[76:77], v[224:225]
	v_pk_fma_f32 v[226:227], v[122:123], v[78:79], v[226:227]
	v_pk_mul_f32 v[190:191], v[220:221], s[100:101] op_sel_hi:[1,0]
	v_pk_mul_f32 v[250:251], v[222:223], s[100:101] op_sel_hi:[1,0]
	v_exp_f32_e32 v190, v190
	v_exp_f32_e32 v191, v191
	v_exp_f32_e32 v250, v250
	v_exp_f32_e32 v251, v251
	v_pk_mul_f32 v[220:221], v[220:221], v[224:225]
	v_pk_mul_f32 v[222:223], v[222:223], v[226:227]
	v_pk_add_f32 v[190:191], v[190:191], 1.0 op_sel_hi:[1,0]
	v_pk_add_f32 v[250:251], v[250:251], 1.0 op_sel_hi:[1,0]
	v_rcp_f32_e32 v190, v190
	v_rcp_f32_e32 v191, v191
	v_rcp_f32_e32 v250, v250
	v_rcp_f32_e32 v251, v251
	v_pk_mul_f32 v[220:221], v[220:221], v[190:191]
	v_pk_mul_f32 v[222:223], v[222:223], v[250:251]
	v_cvt_pk_bf16_f32 v162, v220, v221
	v_cvt_pk_bf16_f32 v163, v222, v223
	v_add_u32_e32 v243, 0xb0000, v239
	global_store_dwordx4 v243, v[160:163], s[24:25]
	v_pk_fma_f32 v[220:221], v[108:109], v[20:21], v[100:101]
	v_pk_fma_f32 v[222:223], v[110:111], v[22:23], v[102:103]
	v_pk_fma_f32 v[224:225], v[104:105], v[16:17], v[96:97]
	v_pk_fma_f32 v[226:227], v[106:107], v[18:19], v[98:99]
	s_mov_b64 exec, s[42:43]
	ds_read_b64 v[72:73], v235
	ds_read_b64 v[74:75], v235 offset:8
	ds_read_b64 v[76:77], v237
	ds_read_b64 v[78:79], v237 offset:8
	s_mov_b64 exec, -1
	ds_write_b128 v212, v[20:23]
	s_mov_b64 exec, s[44:45]
	ds_read_b64 v[72:73], v235
	ds_read_b64 v[74:75], v235 offset:8
	s_mov_b64 exec, s[82:83]
	ds_read_b64 v[76:77], v237
	ds_read_b64 v[78:79], v237 offset:8
	s_mov_b64 exec, -1
	s_waitcnt lgkmcnt(0)
	v_pk_fma_f32 v[220:221], v[116:117], v[72:73], v[220:221]
	v_pk_fma_f32 v[222:223], v[118:119], v[74:75], v[222:223]
	v_pk_fma_f32 v[220:221], v[124:125], v[76:77], v[220:221]
	v_pk_fma_f32 v[222:223], v[126:127], v[78:79], v[222:223]
	s_mov_b64 exec, s[42:43]
	ds_read_b64 v[72:73], v235 offset:8192
	ds_read_b64 v[74:75], v235 offset:8200
	ds_read_b64 v[76:77], v237 offset:8192
	ds_read_b64 v[78:79], v237 offset:8200
	s_mov_b64 exec, -1
	ds_write_b128 v212, v[16:19] offset:8192
	s_mov_b64 exec, s[44:45]
	ds_read_b64 v[72:73], v235 offset:8192
	ds_read_b64 v[74:75], v235 offset:8200
	s_mov_b64 exec, s[82:83]
	ds_read_b64 v[76:77], v237 offset:8192
	ds_read_b64 v[78:79], v237 offset:8200
	s_mov_b64 exec, -1
	s_waitcnt lgkmcnt(0)
	v_pk_fma_f32 v[224:225], v[112:113], v[72:73], v[224:225]
	v_pk_fma_f32 v[226:227], v[114:115], v[74:75], v[226:227]
	v_pk_fma_f32 v[224:225], v[120:121], v[76:77], v[224:225]
	v_pk_fma_f32 v[226:227], v[122:123], v[78:79], v[226:227]
	v_pk_mul_f32 v[190:191], v[220:221], s[100:101] op_sel_hi:[1,0]
	v_pk_mul_f32 v[250:251], v[222:223], s[100:101] op_sel_hi:[1,0]
	v_exp_f32_e32 v190, v190
	v_exp_f32_e32 v191, v191
	v_exp_f32_e32 v250, v250
	v_exp_f32_e32 v251, v251
	v_pk_mul_f32 v[220:221], v[220:221], v[224:225]
	v_pk_mul_f32 v[222:223], v[222:223], v[226:227]
	v_pk_add_f32 v[190:191], v[190:191], 1.0 op_sel_hi:[1,0]
	v_pk_add_f32 v[250:251], v[250:251], 1.0 op_sel_hi:[1,0]
	v_rcp_f32_e32 v190, v190
	v_rcp_f32_e32 v191, v191
	v_rcp_f32_e32 v250, v250
	v_rcp_f32_e32 v251, v251
	v_pk_mul_f32 v[220:221], v[220:221], v[190:191]
	v_pk_mul_f32 v[222:223], v[222:223], v[250:251]
	v_cvt_pk_bf16_f32 v166, v220, v221
	v_cvt_pk_bf16_f32 v167, v222, v223
	v_add_u32_e32 v243, 0xc6000, v239
	global_store_dwordx4 v243, v[164:167], s[24:25]
	v_pk_fma_f32 v[220:221], v[108:109], v[12:13], v[100:101]
	v_pk_fma_f32 v[222:223], v[110:111], v[14:15], v[102:103]
	v_pk_fma_f32 v[224:225], v[104:105], v[8:9], v[96:97]
	v_pk_fma_f32 v[226:227], v[106:107], v[10:11], v[98:99]
	s_mov_b64 exec, s[42:43]
	ds_read_b64 v[72:73], v235
	ds_read_b64 v[74:75], v235 offset:8
	ds_read_b64 v[76:77], v237
	ds_read_b64 v[78:79], v237 offset:8
	s_mov_b64 exec, -1
	ds_write_b128 v212, v[12:15]
	s_mov_b64 exec, s[44:45]
	ds_read_b64 v[72:73], v235
	ds_read_b64 v[74:75], v235 offset:8
	s_mov_b64 exec, s[82:83]
	ds_read_b64 v[76:77], v237
	ds_read_b64 v[78:79], v237 offset:8
	s_mov_b64 exec, -1
	s_waitcnt lgkmcnt(0)
; __device__ __forceinline__ float row_rstd(const float* slots, int row) {
;     const f32x4* s = (const f32x4*)(slots + (size_t)row * 16);
;     const f32x4 a = s[0], b = s[1], c = s[2], d = s[3];
;     const f32x4 t = (a + b) + (c + d);
;     const float ss = (t[0] + t[1]) + (t[2] + t[3]);
;     return __builtin_amdgcn_rsqf(ss * (1.0f / 1024.0f) + 1e-6f);
; }
; __device__ __forceinline__ void load_rs(const float* slots, int rowbase, int fr, int fq, float scale, float (&rs)[2][4]) {
;     float loc[2];
; #pragma unroll
;     for (int ai = 0; ai < 2; ++ai) loc[ai] = scale * row_rstd(slots, rowbase + ai * HALF + fq * 16 + fr);
; #pragma unroll
;     for (int ai = 0; ai < 2; ++ai)
; #pragma unroll
;         for (int m = 0; m < 4; ++m) rs[ai][m] = __shfl(loc[ai], m * 16 + fr);
;     __device__ __forceinline__ void operator()(const f32x4 (&acc)[2][2][4][2], const Unit& u, int wr, int wc, int fr, int fq) const {
;     ...
;                 for (int m = 0; m < 4; ++m) {
;                     f32x4 cur[2], h[2];
; #pragma unroll
;                     for (int bj = 0; bj < 2; ++bj) { cur[bj] = acc[ai][bj][m][n] * rs[ai][m]; f32x4 x1, x2;
; #pragma unroll
;                         for (int e = 0; e < 4; ++e) { const float c1 = dpp_ror1(cur[bj][e]), p1 = dpp_ror1(pg[bj][e]), c2 = dpp_ror2(cur[bj][e]), p2 = dpp_ror2(pg[bj][e]);
;                             x1[e] = fr >= 1 ? c1 : p1; x2[e] = fr >= 2 ? c2 : p2; }
;                         h[bj] = bb[bj] + w0[bj] * x2 + w1[bj] * x1 + w2[bj] * cur[bj]; }
;                     if (ai == 0 && wr == 0 && m == 0 && fr < 2) {
;                         *(f32x4*)(hc0 + (size_t)(u.pm * 2 + fr) * FF2 + gcol + 4 * n) = h[0]; *(f32x4*)(hc0 + (size_t)(u.pm * 2 + fr) * FF2 + FF + gcol + 4 * n) = h[1]; }
;                     f32x4 a;
; #pragma unroll
;                     for (int e = 0; e < 4; ++e) { const float g = h[0][e]; a[e] = g * __builtin_amdgcn_rcpf(1.0f + __builtin_amdgcn_exp2f(-1.4426950408889634f * g)) * h[1][e]; }
;                     const unsigned p0 = cvt_pk_bf16(a[0], a[1]), p1 = cvt_pk_bf16(a[2], a[3]);
;                     if (n == 0) { pk_lo[ai][m][0] = p0; pk_lo[ai][m][1] = p1; }
;                     else { u32x4 w; w.x = pk_lo[ai][m][0]; w.y = pk_lo[ai][m][1]; w.z = p0; w.w = p1;
;                         *(u32x4*)(act + (size_t)(u.pm * BM + ai * HALF + wr * 64 + m * 16 + fr) * FF + gcol) = w; }
	v_pk_fma_f32 v[220:221], v[116:117], v[72:73], v[220:221]
	v_pk_fma_f32 v[222:223], v[118:119], v[74:75], v[222:223]
	v_pk_fma_f32 v[220:221], v[124:125], v[76:77], v[220:221]
	v_pk_fma_f32 v[222:223], v[126:127], v[78:79], v[222:223]
	s_mov_b64 exec, s[42:43]
	ds_read_b64 v[72:73], v235 offset:8192
	ds_read_b64 v[74:75], v235 offset:8200
	ds_read_b64 v[76:77], v237 offset:8192
	ds_read_b64 v[78:79], v237 offset:8200
	s_mov_b64 exec, -1
	ds_write_b128 v212, v[8:11] offset:8192
	s_mov_b64 exec, s[44:45]
	ds_read_b64 v[72:73], v235 offset:8192
	ds_read_b64 v[74:75], v235 offset:8200
	s_mov_b64 exec, s[82:83]
	ds_read_b64 v[76:77], v237 offset:8192
	ds_read_b64 v[78:79], v237 offset:8200
	s_mov_b64 exec, -1
	s_waitcnt lgkmcnt(0)
	v_pk_fma_f32 v[224:225], v[112:113], v[72:73], v[224:225]
	v_pk_fma_f32 v[226:227], v[114:115], v[74:75], v[226:227]
	v_pk_fma_f32 v[224:225], v[120:121], v[76:77], v[224:225]
	v_pk_fma_f32 v[226:227], v[122:123], v[78:79], v[226:227]
	v_pk_mul_f32 v[190:191], v[220:221], s[100:101] op_sel_hi:[1,0]
	v_pk_mul_f32 v[250:251], v[222:223], s[100:101] op_sel_hi:[1,0]
	v_exp_f32_e32 v190, v190
	v_exp_f32_e32 v191, v191
	v_exp_f32_e32 v250, v250
	v_exp_f32_e32 v251, v251
	v_pk_mul_f32 v[220:221], v[220:221], v[224:225]
	v_pk_mul_f32 v[222:223], v[222:223], v[226:227]
	v_pk_add_f32 v[190:191], v[190:191], 1.0 op_sel_hi:[1,0]
	v_pk_add_f32 v[250:251], v[250:251], 1.0 op_sel_hi:[1,0]
	v_rcp_f32_e32 v190, v190
	v_rcp_f32_e32 v191, v191
	v_rcp_f32_e32 v250, v250
	v_rcp_f32_e32 v251, v251
	v_pk_mul_f32 v[220:221], v[220:221], v[190:191]
	v_pk_mul_f32 v[222:223], v[222:223], v[250:251]
	v_cvt_pk_bf16_f32 v180, v220, v221
	v_cvt_pk_bf16_f32 v181, v222, v223
	v_add_u32_e32 v243, 0xdc000, v239
	global_store_dwordx4 v243, v[178:181], s[24:25]
	v_pk_fma_f32 v[220:221], v[108:109], v[4:5], v[100:101]
	v_pk_fma_f32 v[222:223], v[110:111], v[6:7], v[102:103]
	v_pk_fma_f32 v[224:225], v[104:105], v[0:1], v[96:97]
	v_pk_fma_f32 v[226:227], v[106:107], v[2:3], v[98:99]
	s_mov_b64 exec, s[42:43]
	ds_read_b64 v[72:73], v235
	ds_read_b64 v[74:75], v235 offset:8
	ds_read_b64 v[76:77], v237
	ds_read_b64 v[78:79], v237 offset:8
	s_mov_b64 exec, -1
	ds_write_b128 v212, v[4:7]
	s_mov_b64 exec, s[44:45]
	ds_read_b64 v[72:73], v235
	ds_read_b64 v[74:75], v235 offset:8
	s_mov_b64 exec, s[82:83]
	ds_read_b64 v[76:77], v237
	ds_read_b64 v[78:79], v237 offset:8
	s_mov_b64 exec, -1
	s_waitcnt lgkmcnt(0)
	v_pk_fma_f32 v[220:221], v[116:117], v[72:73], v[220:221]
	v_pk_fma_f32 v[222:223], v[118:119], v[74:75], v[222:223]
	v_pk_fma_f32 v[220:221], v[124:125], v[76:77], v[220:221]
	v_pk_fma_f32 v[222:223], v[126:127], v[78:79], v[222:223]
	s_mov_b64 exec, s[42:43]
	ds_read_b64 v[72:73], v235 offset:8192
	ds_read_b64 v[74:75], v235 offset:8200
	ds_read_b64 v[76:77], v237 offset:8192
	ds_read_b64 v[78:79], v237 offset:8200
	s_mov_b64 exec, -1
	ds_write_b128 v212, v[0:3] offset:8192
	s_mov_b64 exec, s[44:45]
	ds_read_b64 v[72:73], v235 offset:8192
	ds_read_b64 v[74:75], v235 offset:8200
	s_mov_b64 exec, s[82:83]
	ds_read_b64 v[76:77], v237 offset:8192
	ds_read_b64 v[78:79], v237 offset:8200
	s_mov_b64 exec, -1
	s_waitcnt lgkmcnt(0)
	v_pk_fma_f32 v[224:225], v[112:113], v[72:73], v[224:225]
	v_pk_fma_f32 v[226:227], v[114:115], v[74:75], v[226:227]
	v_pk_fma_f32 v[224:225], v[120:121], v[76:77], v[224:225]
	v_pk_fma_f32 v[226:227], v[122:123], v[78:79], v[226:227]
	v_pk_mul_f32 v[190:191], v[220:221], s[100:101] op_sel_hi:[1,0]
	v_pk_mul_f32 v[250:251], v[222:223], s[100:101] op_sel_hi:[1,0]
	v_exp_f32_e32 v190, v190
	v_exp_f32_e32 v191, v191
	v_exp_f32_e32 v250, v250
	v_exp_f32_e32 v251, v251
	v_pk_mul_f32 v[220:221], v[220:221], v[224:225]
	v_pk_mul_f32 v[222:223], v[222:223], v[226:227]
	v_pk_add_f32 v[190:191], v[190:191], 1.0 op_sel_hi:[1,0]
	v_pk_add_f32 v[250:251], v[250:251], 1.0 op_sel_hi:[1,0]
	v_rcp_f32_e32 v190, v190
	v_rcp_f32_e32 v191, v191
	v_rcp_f32_e32 v250, v250
	v_rcp_f32_e32 v251, v251
	v_pk_mul_f32 v[220:221], v[220:221], v[190:191]
	v_pk_mul_f32 v[222:223], v[222:223], v[250:251]
	v_cvt_pk_bf16_f32 v184, v220, v221
	v_cvt_pk_bf16_f32 v185, v222, v223
	v_add_u32_e32 v243, 0xf2000, v239
	global_store_dwordx4 v243, v[182:185], s[24:25]
	s_cmp_eq_u32 s79, 0
	s_cbranch_scc1 .Lp7_nored
	s_waitcnt vmcnt(4)
	v_lshlrev_b32_e32 v237, 2, v206
	v_pk_add_f32 v[62:63], v[62:63], v[54:55]
	v_pk_add_f32 v[58:59], v[58:59], v[50:51]
	v_pk_add_f32 v[60:61], v[60:61], v[52:53]
	v_pk_add_f32 v[56:57], v[56:57], v[48:49]
	v_pk_add_f32 v[52:53], v[46:47], v[38:39]
	v_pk_add_f32 v[48:49], v[42:43], v[34:35]
	v_pk_add_f32 v[54:55], v[44:45], v[36:37]
	v_pk_add_f32 v[50:51], v[40:41], v[32:33]
	v_pk_add_f32 v[62:63], v[62:63], v[52:53]
	v_pk_add_f32 v[58:59], v[58:59], v[48:49]
	v_pk_add_f32 v[60:61], v[60:61], v[54:55]
	v_pk_add_f32 v[56:57], v[56:57], v[50:51]
	v_add_f32_e32 v60, v60, v61
	v_add_f32_e32 v56, v56, v57
	v_add_f32_e32 v61, v62, v63
	v_add_f32_e32 v57, v58, v59
	v_add_f32_e32 v60, v60, v61
	v_add_f32_e32 v56, v56, v57
	v_fmamk_f32 v60, v60, 0x3a800000, v244
	v_fmamk_f32 v56, v56, 0x3a800000, v244
	v_rsq_f32_e32 v60, v60
	v_rsq_f32_e32 v56, v56
	ds_bpermute_b32 v228, v237, v60
	ds_bpermute_b32 v230, v237, v60 offset:64
	ds_bpermute_b32 v232, v237, v60 offset:128
	ds_bpermute_b32 v234, v237, v60 offset:192
	ds_bpermute_b32 v236, v237, v56
	ds_bpermute_b32 v238, v237, v56 offset:64
	ds_bpermute_b32 v240, v237, v56 offset:128
	ds_bpermute_b32 v248, v237, v56 offset:192
	s_mov_b32 s101, s10
